# norm1 phase pipelined like norm2; out-proj tile start no longer drains the first K-tile loads before zeroing accumulators
# baseline (speedup 1.0000x reference)
; __device__ __forceinline__ void norm_phase(const float* H, const float* g, bf16_t* HN) {
;     ...
;   for (int row = gw; row < NREAL + 64; row += 2 * nw) {
;     const int row2 = row + nw < NREAL + 64 ? row + nw : row;
;     const float* p = H + (size_t)row * DM + lane * 8; const float* p2 = H + (size_t)row2 * DM + lane * 8; f32x4 v[4], u[4]; float ss = 0.f, ss2 = 0.f;
; #pragma unroll
;     for (int i = 0; i < 4; ++i) { v[i] = *(const f32x4*)(p + 512 * (i >> 1) + 4 * (i & 1)); u[i] = *(const f32x4*)(p2 + 512 * (i >> 1) + 4 * (i & 1)); }
; #pragma unroll
;     for (int i = 0; i < 4; ++i) { ss += v[i][0] * v[i][0] + v[i][1] * v[i][1] + v[i][2] * v[i][2] + v[i][3] * v[i][3]; ss2 += u[i][0] * u[i][0] + u[i][1] * u[i][1] + u[i][2] * u[i][2] + u[i][3] * u[i][3]; }
;     ss = wave_sum(ss); ss2 = wave_sum(ss2); const float rs = rsqrtf(ss * (1.0f / 1024.0f) + 1e-6f), rs2 = rsqrtf(ss2 * (1.0f / 1024.0f) + 1e-6f);
.LBB0_224:
	v_readfirstlane_b32 s0, v22
	s_nop 3
	s_lshl_b32 s9, s8, 1
	s_add_i32 s11, s0, s8
	s_cmp_lt_i32 s11, s49
	s_cselect_b32 s11, s11, s0
	s_lshl_b32 s12, s0, 12
	s_lshl_b32 s13, s11, 12
	v_mov_b32_e32 v62, s12
	v_mov_b32_e32 v63, 0
	v_lshl_add_u64 v[60:61], v[18:19], 0, v[62:63]
	v_mov_b32_e32 v62, s13
	v_lshl_add_u64 v[64:65], v[18:19], 0, v[62:63]
	global_load_dwordx4 v[26:29], v[60:61], off
	global_load_dwordx4 v[30:33], v[60:61], off offset:16
	global_load_dwordx4 v[34:37], v[60:61], off offset:2048
	global_load_dwordx4 v[38:41], v[60:61], off offset:2064
	global_load_dwordx4 v[42:45], v[64:65], off
	global_load_dwordx4 v[46:49], v[64:65], off offset:16
	global_load_dwordx4 v[50:53], v[64:65], off offset:2048
	global_load_dwordx4 v[54:57], v[64:65], off offset:2064
	s_lshl_b32 s12, s0, 11
	s_lshl_b32 s13, s11, 11
	v_mov_b32_e32 v62, s12
	v_lshl_add_u64 v[24:25], v[20:21], 0, v[62:63]
	v_mov_b32_e32 v62, s13
	v_lshl_add_u64 v[58:59], v[20:21], 0, v[62:63]
	s_add_i32 s1, s0, s9
	s_cmp_lt_i32 s1, s49
	s_cbranch_scc0 .Ln1_lastA_first
	s_add_i32 s11, s1, s8
	s_cmp_lt_i32 s11, s49
	s_cselect_b32 s11, s11, s1
	s_lshl_b32 s12, s1, 12
	s_lshl_b32 s13, s11, 12
	v_mov_b32_e32 v62, s12
	v_mov_b32_e32 v63, 0
	v_lshl_add_u64 v[60:61], v[18:19], 0, v[62:63]
	v_mov_b32_e32 v62, s13
	v_lshl_add_u64 v[64:65], v[18:19], 0, v[62:63]
	global_load_dwordx4 v[72:75], v[60:61], off
	global_load_dwordx4 v[76:79], v[60:61], off offset:16
	global_load_dwordx4 v[80:83], v[60:61], off offset:2048
	global_load_dwordx4 v[88:91], v[60:61], off offset:2064
	global_load_dwordx4 v[92:95], v[64:65], off
	global_load_dwordx4 v[96:99], v[64:65], off offset:16
	global_load_dwordx4 v[100:103], v[64:65], off offset:2048
	global_load_dwordx4 v[128:131], v[64:65], off offset:2064
	s_lshl_b32 s12, s1, 11
	s_lshl_b32 s13, s11, 11
	v_mov_b32_e32 v62, s12
	v_lshl_add_u64 v[132:133], v[20:21], 0, v[62:63]
	v_mov_b32_e32 v62, s13
	v_lshl_add_u64 v[134:135], v[20:21], 0, v[62:63]
	s_waitcnt vmcnt(8)
	v_lshlrev_b32_e32 v0, 2, v210
	v_xor_b32_e32 v0, 0x80, v0
	v_mov_b32_e32 v23, v0
	v_mov_b32_e32 v62, v27
	v_mov_b32_e32 v63, v31
	v_mov_b32_e32 v70, v35
	v_mov_b32_e32 v71, v39
	v_mov_b32_e32 v60, v26
	v_mov_b32_e32 v61, v30
	v_mov_b32_e32 v68, v34
	v_mov_b32_e32 v69, v38
	v_pk_mul_f32 v[62:63], v[62:63], v[62:63]
	v_pk_mul_f32 v[70:71], v[70:71], v[70:71]
	v_pk_fma_f32 v[60:61], v[60:61], v[60:61], v[62:63]
	v_mov_b32_e32 v62, v36
	v_mov_b32_e32 v63, v40
	v_pk_fma_f32 v[68:69], v[68:69], v[68:69], v[70:71]
	v_mov_b32_e32 v64, v28
	v_mov_b32_e32 v65, v32
	v_mov_b32_e32 v70, v37
	v_mov_b32_e32 v71, v41
	v_pk_fma_f32 v[62:63], v[62:63], v[62:63], v[68:69]
	v_mov_b32_e32 v68, v43
	v_mov_b32_e32 v69, v47
	v_mov_b32_e32 v66, v29
	v_mov_b32_e32 v67, v33
	v_pk_fma_f32 v[60:61], v[64:65], v[64:65], v[60:61]
	v_mov_b32_e32 v64, v42
	v_mov_b32_e32 v65, v46
	v_pk_mul_f32 v[68:69], v[68:69], v[68:69]
	v_pk_fma_f32 v[62:63], v[70:71], v[70:71], v[62:63]
	v_mov_b32_e32 v70, v51
	v_mov_b32_e32 v71, v55
	v_pk_fma_f32 v[60:61], v[66:67], v[66:67], v[60:61]
	v_mov_b32_e32 v66, v44
	v_mov_b32_e32 v67, v48
	v_pk_fma_f32 v[64:65], v[64:65], v[64:65], v[68:69]
	v_mov_b32_e32 v68, v50
	v_mov_b32_e32 v69, v54
	v_pk_mul_f32 v[70:71], v[70:71], v[70:71]
	v_pk_fma_f32 v[64:65], v[66:67], v[66:67], v[64:65]
	v_pk_fma_f32 v[68:69], v[68:69], v[68:69], v[70:71]
	v_mov_b32_e32 v70, v45
	v_mov_b32_e32 v71, v49
	v_mov_b32_e32 v66, v52
	v_mov_b32_e32 v67, v56
	v_pk_fma_f32 v[66:67], v[66:67], v[66:67], v[68:69]
	v_mov_b32_e32 v68, v53
	v_mov_b32_e32 v69, v57
	v_pk_fma_f32 v[64:65], v[70:71], v[70:71], v[64:65]
	v_mov_b32_e32 v71, v60
	v_pk_fma_f32 v[66:67], v[68:69], v[68:69], v[66:67]
	v_mov_b32_e32 v70, v64
	v_mov_b32_e32 v60, v65
	v_mov_b32_e32 v69, v62
	v_mov_b32_e32 v68, v66
	v_pk_add_f32 v[60:61], v[70:71], v[60:61]
	v_mov_b32_e32 v62, v67
	v_pk_add_f32 v[60:61], v[60:61], v[68:69]
	s_nop 0
	v_pk_add_f32 v[60:61], v[60:61], v[62:63]
	ds_swizzle_b32 v63, v61 offset:swizzle(SWAP,16)
	ds_swizzle_b32 v62, v60 offset:swizzle(SWAP,16)
	s_waitcnt lgkmcnt(0)
	v_pk_add_f32 v[60:61], v[60:61], v[62:63]
	ds_swizzle_b32 v63, v61 offset:swizzle(SWAP,8)
	ds_swizzle_b32 v62, v60 offset:swizzle(SWAP,8)
	s_waitcnt lgkmcnt(0)
	v_pk_add_f32 v[60:61], v[60:61], v[62:63]
	ds_swizzle_b32 v63, v61 offset:swizzle(SWAP,4)
	ds_swizzle_b32 v62, v60 offset:swizzle(SWAP,4)
	s_waitcnt lgkmcnt(0)
	v_pk_add_f32 v[60:61], v[60:61], v[62:63]
	ds_swizzle_b32 v63, v61 offset:swizzle(SWAP,2)
	ds_swizzle_b32 v62, v60 offset:swizzle(SWAP,2)
	s_waitcnt lgkmcnt(0)
	v_pk_add_f32 v[60:61], v[60:61], v[62:63]
	ds_swizzle_b32 v63, v61 offset:swizzle(SWAP,1)
	ds_swizzle_b32 v62, v60 offset:swizzle(SWAP,1)
	s_waitcnt lgkmcnt(0)
	v_pk_add_f32 v[60:61], v[60:61], v[62:63]
	ds_bpermute_b32 v63, v0, v61
	ds_bpermute_b32 v62, v23, v60
	s_waitcnt lgkmcnt(0)
; __device__ __forceinline__ void store8bf(bf16_t* p, f32x4 v0, f32x4 v1) { u32x4 w; w.x = cvt_pk_bf16(v0[0], v0[1]); w.y = cvt_pk_bf16(v0[2], v0[3]); w.z = cvt_pk_bf16(v1[0], v1[1]); w.w = cvt_pk_bf16(v1[2], v1[3]); *(u32x4*)p = w; }
; __device__ __forceinline__ void norm_phase(const float* H, const float* g, bf16_t* HN) {
;     ...
;     ss = wave_sum(ss); ss2 = wave_sum(ss2); const float rs = rsqrtf(ss * (1.0f / 1024.0f) + 1e-6f), rs2 = rsqrtf(ss2 * (1.0f / 1024.0f) + 1e-6f);
;     bf16_t* q = HN + (size_t)row * DM + lane * 8; bf16_t* q2 = HN + (size_t)row2 * DM + lane * 8;
; #pragma unroll
;     for (int i = 0; i < 2; ++i) { store8bf(q + 512 * i, v[2 * i] * rs * gv[2 * i], v[2 * i + 1] * rs * gv[2 * i + 1]); store8bf(q2 + 512 * i, u[2 * i] * rs2 * gv[2 * i], u[2 * i + 1] * rs2 * gv[2 * i + 1]); }
;   }
	v_pk_add_f32 v[60:61], v[60:61], v[62:63]
	s_nop 0
	v_pk_fma_f32 v[60:61], v[60:61], s[58:59], v[154:155] op_sel_hi:[1,0,0]
	s_nop 0
	v_mul_f32_e32 v0, 0x4b800000, v61
	v_cmp_gt_f32_e64 s[2:3], s46, v61
	v_mul_f32_e32 v23, 0x4b800000, v60
	v_cmp_gt_f32_e32 vcc, s46, v60
	v_cndmask_b32_e64 v0, v61, v0, s[2:3]
	v_rsq_f32_e32 v0, v0
	v_cndmask_b32_e32 v23, v60, v23, vcc
	v_rsq_f32_e32 v23, v23
	v_mul_f32_e32 v60, 0x45800000, v0
	v_cndmask_b32_e64 v0, v0, v60, s[2:3]
	v_mul_f32_e32 v61, 0x45800000, v23
	v_cndmask_b32_e32 v60, v23, v61, vcc
	v_pk_mul_f32 v[26:27], v[26:27], v[0:1] op_sel_hi:[1,0]
	v_pk_mul_f32 v[28:29], v[28:29], v[0:1] op_sel_hi:[1,0]
	v_pk_mul_f32 v[30:31], v[30:31], v[0:1] op_sel_hi:[1,0]
	v_pk_mul_f32 v[32:33], v[32:33], v[0:1] op_sel_hi:[1,0]
	v_pk_mul_f32 v[42:43], v[42:43], v[60:61] op_sel_hi:[1,0]
	v_pk_mul_f32 v[44:45], v[44:45], v[60:61] op_sel_hi:[1,0]
	v_pk_mul_f32 v[46:47], v[46:47], v[60:61] op_sel_hi:[1,0]
	v_pk_mul_f32 v[48:49], v[48:49], v[60:61] op_sel_hi:[1,0]
	v_pk_mul_f32 v[34:35], v[34:35], v[0:1] op_sel_hi:[1,0]
	v_pk_mul_f32 v[36:37], v[36:37], v[0:1] op_sel_hi:[1,0]
	v_pk_mul_f32 v[38:39], v[38:39], v[0:1] op_sel_hi:[1,0]
	v_pk_mul_f32 v[40:41], v[40:41], v[0:1] op_sel_hi:[1,0]
	v_pk_mul_f32 v[50:51], v[50:51], v[60:61] op_sel_hi:[1,0]
	v_pk_mul_f32 v[52:53], v[52:53], v[60:61] op_sel_hi:[1,0]
	v_pk_mul_f32 v[54:55], v[54:55], v[60:61] op_sel_hi:[1,0]
	v_pk_mul_f32 v[56:57], v[56:57], v[60:61] op_sel_hi:[1,0]
	v_pk_mul_f32 v[28:29], v[8:9], v[28:29]
	v_pk_mul_f32 v[26:27], v[6:7], v[26:27]
	v_pk_mul_f32 v[32:33], v[4:5], v[32:33]
	v_pk_mul_f32 v[30:31], v[2:3], v[30:31]
	v_pk_mul_f32 v[44:45], v[8:9], v[44:45]
	v_pk_mul_f32 v[42:43], v[6:7], v[42:43]
	v_pk_mul_f32 v[48:49], v[4:5], v[48:49]
	v_pk_mul_f32 v[46:47], v[2:3], v[46:47]
	v_pk_mul_f32 v[36:37], v[16:17], v[36:37]
	v_pk_mul_f32 v[34:35], v[14:15], v[34:35]
	v_pk_mul_f32 v[40:41], v[12:13], v[40:41]
	v_pk_mul_f32 v[38:39], v[10:11], v[38:39]
	v_pk_mul_f32 v[52:53], v[16:17], v[52:53]
	v_pk_mul_f32 v[50:51], v[14:15], v[50:51]
	v_pk_mul_f32 v[56:57], v[12:13], v[56:57]
	v_pk_mul_f32 v[54:55], v[10:11], v[54:55]
	v_cvt_pk_bf16_f32 v26, v26, v27
	v_cvt_pk_bf16_f32 v27, v28, v29
	v_cvt_pk_bf16_f32 v28, v30, v31
	v_cvt_pk_bf16_f32 v29, v32, v33
	v_cvt_pk_bf16_f32 v30, v42, v43
	v_cvt_pk_bf16_f32 v31, v44, v45
	v_cvt_pk_bf16_f32 v32, v46, v47
	v_cvt_pk_bf16_f32 v33, v48, v49
	v_cvt_pk_bf16_f32 v34, v34, v35
	v_cvt_pk_bf16_f32 v35, v36, v37
	v_cvt_pk_bf16_f32 v36, v38, v39
	v_cvt_pk_bf16_f32 v37, v40, v41
	v_cvt_pk_bf16_f32 v38, v50, v51
	v_cvt_pk_bf16_f32 v39, v52, v53
	v_cvt_pk_bf16_f32 v40, v54, v55
	v_cvt_pk_bf16_f32 v41, v56, v57
	global_store_dwordx4 v[24:25], v[26:29], off
	global_store_dwordx4 v[58:59], v[30:33], off
	global_store_dwordx4 v[24:25], v[34:37], off offset:1024
	global_store_dwordx4 v[58:59], v[38:41], off offset:1024
.Ln1_loop:
	s_add_i32 s0, s1, s9
	s_cmp_lt_i32 s0, s49
	s_cbranch_scc0 .Ln1_lastB
	s_add_i32 s11, s0, s8
	s_cmp_lt_i32 s11, s49
	s_cselect_b32 s11, s11, s0
	s_lshl_b32 s12, s0, 12
	s_lshl_b32 s13, s11, 12
	v_mov_b32_e32 v62, s12
	v_mov_b32_e32 v63, 0
	v_lshl_add_u64 v[60:61], v[18:19], 0, v[62:63]
	v_mov_b32_e32 v62, s13
	v_lshl_add_u64 v[64:65], v[18:19], 0, v[62:63]
	global_load_dwordx4 v[26:29], v[60:61], off
	global_load_dwordx4 v[30:33], v[60:61], off offset:16
	global_load_dwordx4 v[34:37], v[60:61], off offset:2048
	global_load_dwordx4 v[38:41], v[60:61], off offset:2064
	global_load_dwordx4 v[42:45], v[64:65], off
	global_load_dwordx4 v[46:49], v[64:65], off offset:16
	global_load_dwordx4 v[50:53], v[64:65], off offset:2048
	global_load_dwordx4 v[54:57], v[64:65], off offset:2064
	s_lshl_b32 s12, s0, 11
	s_lshl_b32 s13, s11, 11
	v_mov_b32_e32 v62, s12
	v_lshl_add_u64 v[24:25], v[20:21], 0, v[62:63]
	v_mov_b32_e32 v62, s13
	v_lshl_add_u64 v[58:59], v[20:21], 0, v[62:63]
	s_waitcnt vmcnt(12)
	v_lshlrev_b32_e32 v0, 2, v210
	v_xor_b32_e32 v0, 0x80, v0
	v_mov_b32_e32 v23, v0
	v_mov_b32_e32 v62, v73
	v_mov_b32_e32 v63, v77
	v_mov_b32_e32 v70, v81
	v_mov_b32_e32 v71, v89
	v_mov_b32_e32 v60, v72
	v_mov_b32_e32 v61, v76
	v_mov_b32_e32 v68, v80
	v_mov_b32_e32 v69, v88
	v_pk_mul_f32 v[62:63], v[62:63], v[62:63]
	v_pk_mul_f32 v[70:71], v[70:71], v[70:71]
	v_pk_fma_f32 v[60:61], v[60:61], v[60:61], v[62:63]
	v_mov_b32_e32 v62, v82
	v_mov_b32_e32 v63, v90
	v_pk_fma_f32 v[68:69], v[68:69], v[68:69], v[70:71]
	v_mov_b32_e32 v64, v74
	v_mov_b32_e32 v65, v78
	v_mov_b32_e32 v70, v83
	v_mov_b32_e32 v71, v91
	v_pk_fma_f32 v[62:63], v[62:63], v[62:63], v[68:69]
	v_mov_b32_e32 v68, v93
	v_mov_b32_e32 v69, v97
	v_mov_b32_e32 v66, v75
	v_mov_b32_e32 v67, v79
	v_pk_fma_f32 v[60:61], v[64:65], v[64:65], v[60:61]
	v_mov_b32_e32 v64, v92
	v_mov_b32_e32 v65, v96
	v_pk_mul_f32 v[68:69], v[68:69], v[68:69]
	v_pk_fma_f32 v[62:63], v[70:71], v[70:71], v[62:63]
	v_mov_b32_e32 v70, v101
	v_mov_b32_e32 v71, v129
	v_pk_fma_f32 v[60:61], v[66:67], v[66:67], v[60:61]
	v_mov_b32_e32 v66, v94
	v_mov_b32_e32 v67, v98
	v_pk_fma_f32 v[64:65], v[64:65], v[64:65], v[68:69]
	v_mov_b32_e32 v68, v100
	v_mov_b32_e32 v69, v128
	v_pk_mul_f32 v[70:71], v[70:71], v[70:71]
	v_pk_fma_f32 v[64:65], v[66:67], v[66:67], v[64:65]
	v_pk_fma_f32 v[68:69], v[68:69], v[68:69], v[70:71]
	v_mov_b32_e32 v70, v95
	v_mov_b32_e32 v71, v99
	v_mov_b32_e32 v66, v102
	v_mov_b32_e32 v67, v130
	v_pk_fma_f32 v[66:67], v[66:67], v[66:67], v[68:69]
	v_mov_b32_e32 v68, v103
	v_mov_b32_e32 v69, v131
	v_pk_fma_f32 v[64:65], v[70:71], v[70:71], v[64:65]
	v_mov_b32_e32 v71, v60
	v_pk_fma_f32 v[66:67], v[68:69], v[68:69], v[66:67]
	v_mov_b32_e32 v70, v64
	v_mov_b32_e32 v60, v65
	v_mov_b32_e32 v69, v62
	v_mov_b32_e32 v68, v66
	v_pk_add_f32 v[60:61], v[70:71], v[60:61]
	v_mov_b32_e32 v62, v67
	v_pk_add_f32 v[60:61], v[60:61], v[68:69]
	s_nop 0
	v_pk_add_f32 v[60:61], v[60:61], v[62:63]
	ds_swizzle_b32 v63, v61 offset:swizzle(SWAP,16)
	ds_swizzle_b32 v62, v60 offset:swizzle(SWAP,16)
	s_waitcnt lgkmcnt(0)
; __device__ __forceinline__ void store8bf(bf16_t* p, f32x4 v0, f32x4 v1) { u32x4 w; w.x = cvt_pk_bf16(v0[0], v0[1]); w.y = cvt_pk_bf16(v0[2], v0[3]); w.z = cvt_pk_bf16(v1[0], v1[1]); w.w = cvt_pk_bf16(v1[2], v1[3]); *(u32x4*)p = w; }
; __device__ __forceinline__ void norm_phase(const float* H, const float* g, bf16_t* HN) {
;     ...
;     ss = wave_sum(ss); ss2 = wave_sum(ss2); const float rs = rsqrtf(ss * (1.0f / 1024.0f) + 1e-6f), rs2 = rsqrtf(ss2 * (1.0f / 1024.0f) + 1e-6f);
;     bf16_t* q = HN + (size_t)row * DM + lane * 8; bf16_t* q2 = HN + (size_t)row2 * DM + lane * 8;
; #pragma unroll
;     for (int i = 0; i < 2; ++i) { store8bf(q + 512 * i, v[2 * i] * rs * gv[2 * i], v[2 * i + 1] * rs * gv[2 * i + 1]); store8bf(q2 + 512 * i, u[2 * i] * rs2 * gv[2 * i], u[2 * i + 1] * rs2 * gv[2 * i + 1]); }
;   }
	v_pk_add_f32 v[60:61], v[60:61], v[62:63]
	ds_swizzle_b32 v63, v61 offset:swizzle(SWAP,8)
	ds_swizzle_b32 v62, v60 offset:swizzle(SWAP,8)
	s_waitcnt lgkmcnt(0)
	v_pk_add_f32 v[60:61], v[60:61], v[62:63]
	ds_swizzle_b32 v63, v61 offset:swizzle(SWAP,4)
	ds_swizzle_b32 v62, v60 offset:swizzle(SWAP,4)
	s_waitcnt lgkmcnt(0)
	v_pk_add_f32 v[60:61], v[60:61], v[62:63]
	ds_swizzle_b32 v63, v61 offset:swizzle(SWAP,2)
	ds_swizzle_b32 v62, v60 offset:swizzle(SWAP,2)
	s_waitcnt lgkmcnt(0)
	v_pk_add_f32 v[60:61], v[60:61], v[62:63]
	ds_swizzle_b32 v63, v61 offset:swizzle(SWAP,1)
	ds_swizzle_b32 v62, v60 offset:swizzle(SWAP,1)
	s_waitcnt lgkmcnt(0)
	v_pk_add_f32 v[60:61], v[60:61], v[62:63]
	ds_bpermute_b32 v63, v0, v61
	ds_bpermute_b32 v62, v23, v60
	s_waitcnt lgkmcnt(0)
	v_pk_add_f32 v[60:61], v[60:61], v[62:63]
	s_nop 0
	v_pk_fma_f32 v[60:61], v[60:61], s[58:59], v[154:155] op_sel_hi:[1,0,0]
	s_nop 0
	v_mul_f32_e32 v0, 0x4b800000, v61
	v_cmp_gt_f32_e64 s[2:3], s46, v61
	v_mul_f32_e32 v23, 0x4b800000, v60
	v_cmp_gt_f32_e32 vcc, s46, v60
	v_cndmask_b32_e64 v0, v61, v0, s[2:3]
	v_rsq_f32_e32 v0, v0
	v_cndmask_b32_e32 v23, v60, v23, vcc
	v_rsq_f32_e32 v23, v23
	v_mul_f32_e32 v60, 0x45800000, v0
	v_cndmask_b32_e64 v0, v0, v60, s[2:3]
	v_mul_f32_e32 v61, 0x45800000, v23
	v_cndmask_b32_e32 v60, v23, v61, vcc
	v_pk_mul_f32 v[72:73], v[72:73], v[0:1] op_sel_hi:[1,0]
	v_pk_mul_f32 v[74:75], v[74:75], v[0:1] op_sel_hi:[1,0]
	v_pk_mul_f32 v[76:77], v[76:77], v[0:1] op_sel_hi:[1,0]
	v_pk_mul_f32 v[78:79], v[78:79], v[0:1] op_sel_hi:[1,0]
	v_pk_mul_f32 v[92:93], v[92:93], v[60:61] op_sel_hi:[1,0]
	v_pk_mul_f32 v[94:95], v[94:95], v[60:61] op_sel_hi:[1,0]
	v_pk_mul_f32 v[96:97], v[96:97], v[60:61] op_sel_hi:[1,0]
	v_pk_mul_f32 v[98:99], v[98:99], v[60:61] op_sel_hi:[1,0]
	v_pk_mul_f32 v[80:81], v[80:81], v[0:1] op_sel_hi:[1,0]
	v_pk_mul_f32 v[82:83], v[82:83], v[0:1] op_sel_hi:[1,0]
	v_pk_mul_f32 v[88:89], v[88:89], v[0:1] op_sel_hi:[1,0]
	v_pk_mul_f32 v[90:91], v[90:91], v[0:1] op_sel_hi:[1,0]
	v_pk_mul_f32 v[100:101], v[100:101], v[60:61] op_sel_hi:[1,0]
	v_pk_mul_f32 v[102:103], v[102:103], v[60:61] op_sel_hi:[1,0]
	v_pk_mul_f32 v[128:129], v[128:129], v[60:61] op_sel_hi:[1,0]
	v_pk_mul_f32 v[130:131], v[130:131], v[60:61] op_sel_hi:[1,0]
	v_pk_mul_f32 v[74:75], v[8:9], v[74:75]
	v_pk_mul_f32 v[72:73], v[6:7], v[72:73]
	v_pk_mul_f32 v[78:79], v[4:5], v[78:79]
	v_pk_mul_f32 v[76:77], v[2:3], v[76:77]
	v_pk_mul_f32 v[94:95], v[8:9], v[94:95]
	v_pk_mul_f32 v[92:93], v[6:7], v[92:93]
	v_pk_mul_f32 v[98:99], v[4:5], v[98:99]
	v_pk_mul_f32 v[96:97], v[2:3], v[96:97]
	v_pk_mul_f32 v[82:83], v[16:17], v[82:83]
	v_pk_mul_f32 v[80:81], v[14:15], v[80:81]
	v_pk_mul_f32 v[90:91], v[12:13], v[90:91]
	v_pk_mul_f32 v[88:89], v[10:11], v[88:89]
	v_pk_mul_f32 v[102:103], v[16:17], v[102:103]
	v_pk_mul_f32 v[100:101], v[14:15], v[100:101]
	v_pk_mul_f32 v[130:131], v[12:13], v[130:131]
	v_pk_mul_f32 v[128:129], v[10:11], v[128:129]
	v_cvt_pk_bf16_f32 v72, v72, v73
	v_cvt_pk_bf16_f32 v73, v74, v75
	v_cvt_pk_bf16_f32 v74, v76, v77
	v_cvt_pk_bf16_f32 v75, v78, v79
	v_cvt_pk_bf16_f32 v76, v92, v93
	v_cvt_pk_bf16_f32 v77, v94, v95
	v_cvt_pk_bf16_f32 v78, v96, v97
	v_cvt_pk_bf16_f32 v79, v98, v99
	v_cvt_pk_bf16_f32 v80, v80, v81
	v_cvt_pk_bf16_f32 v81, v82, v83
	v_cvt_pk_bf16_f32 v82, v88, v89
	v_cvt_pk_bf16_f32 v83, v90, v91
	v_cvt_pk_bf16_f32 v88, v100, v101
	v_cvt_pk_bf16_f32 v89, v102, v103
	v_cvt_pk_bf16_f32 v90, v128, v129
	v_cvt_pk_bf16_f32 v91, v130, v131
	global_store_dwordx4 v[132:133], v[72:75], off
	global_store_dwordx4 v[134:135], v[76:79], off
	global_store_dwordx4 v[132:133], v[80:83], off offset:1024
	global_store_dwordx4 v[134:135], v[88:91], off offset:1024
	s_add_i32 s1, s0, s9
	s_cmp_lt_i32 s1, s49
	s_cbranch_scc0 .Ln1_lastA
	s_add_i32 s11, s1, s8
	s_cmp_lt_i32 s11, s49
	s_cselect_b32 s11, s11, s1
	s_lshl_b32 s12, s1, 12
	s_lshl_b32 s13, s11, 12
	v_mov_b32_e32 v62, s12
	v_mov_b32_e32 v63, 0
	v_lshl_add_u64 v[60:61], v[18:19], 0, v[62:63]
	v_mov_b32_e32 v62, s13
	v_lshl_add_u64 v[64:65], v[18:19], 0, v[62:63]
	global_load_dwordx4 v[72:75], v[60:61], off
	global_load_dwordx4 v[76:79], v[60:61], off offset:16
	global_load_dwordx4 v[80:83], v[60:61], off offset:2048
	global_load_dwordx4 v[88:91], v[60:61], off offset:2064
	global_load_dwordx4 v[92:95], v[64:65], off
	global_load_dwordx4 v[96:99], v[64:65], off offset:16
	global_load_dwordx4 v[100:103], v[64:65], off offset:2048
	global_load_dwordx4 v[128:131], v[64:65], off offset:2064
	s_lshl_b32 s12, s1, 11
	s_lshl_b32 s13, s11, 11
	v_mov_b32_e32 v62, s12
	v_lshl_add_u64 v[132:133], v[20:21], 0, v[62:63]
	v_mov_b32_e32 v62, s13
	v_lshl_add_u64 v[134:135], v[20:21], 0, v[62:63]
	s_waitcnt vmcnt(12)
; __device__ __forceinline__ void store8bf(bf16_t* p, f32x4 v0, f32x4 v1) { u32x4 w; w.x = cvt_pk_bf16(v0[0], v0[1]); w.y = cvt_pk_bf16(v0[2], v0[3]); w.z = cvt_pk_bf16(v1[0], v1[1]); w.w = cvt_pk_bf16(v1[2], v1[3]); *(u32x4*)p = w; }
; __device__ __forceinline__ void norm_phase(const float* H, const float* g, bf16_t* HN) {
;     ...
;     const float* p = H + (size_t)row * DM + lane * 8; const float* p2 = H + (size_t)row2 * DM + lane * 8; f32x4 v[4], u[4]; float ss = 0.f, ss2 = 0.f;
; #pragma unroll
;     for (int i = 0; i < 4; ++i) { v[i] = *(const f32x4*)(p + 512 * (i >> 1) + 4 * (i & 1)); u[i] = *(const f32x4*)(p2 + 512 * (i >> 1) + 4 * (i & 1)); }
; #pragma unroll
;     for (int i = 0; i < 4; ++i) { ss += v[i][0] * v[i][0] + v[i][1] * v[i][1] + v[i][2] * v[i][2] + v[i][3] * v[i][3]; ss2 += u[i][0] * u[i][0] + u[i][1] * u[i][1] + u[i][2] * u[i][2] + u[i][3] * u[i][3]; }
;     ss = wave_sum(ss); ss2 = wave_sum(ss2); const float rs = rsqrtf(ss * (1.0f / 1024.0f) + 1e-6f), rs2 = rsqrtf(ss2 * (1.0f / 1024.0f) + 1e-6f);
;     bf16_t* q = HN + (size_t)row * DM + lane * 8; bf16_t* q2 = HN + (size_t)row2 * DM + lane * 8;
; #pragma unroll
;     for (int i = 0; i < 2; ++i) { store8bf(q + 512 * i, v[2 * i] * rs * gv[2 * i], v[2 * i + 1] * rs * gv[2 * i + 1]); store8bf(q2 + 512 * i, u[2 * i] * rs2 * gv[2 * i], u[2 * i + 1] * rs2 * gv[2 * i + 1]); }
	v_lshlrev_b32_e32 v0, 2, v210
	v_xor_b32_e32 v0, 0x80, v0
	v_mov_b32_e32 v23, v0
	v_mov_b32_e32 v62, v27
	v_mov_b32_e32 v63, v31
	v_mov_b32_e32 v70, v35
	v_mov_b32_e32 v71, v39
	v_mov_b32_e32 v60, v26
	v_mov_b32_e32 v61, v30
	v_mov_b32_e32 v68, v34
	v_mov_b32_e32 v69, v38
	v_pk_mul_f32 v[62:63], v[62:63], v[62:63]
	v_pk_mul_f32 v[70:71], v[70:71], v[70:71]
	v_pk_fma_f32 v[60:61], v[60:61], v[60:61], v[62:63]
	v_mov_b32_e32 v62, v36
	v_mov_b32_e32 v63, v40
	v_pk_fma_f32 v[68:69], v[68:69], v[68:69], v[70:71]
	v_mov_b32_e32 v64, v28
	v_mov_b32_e32 v65, v32
	v_mov_b32_e32 v70, v37
	v_mov_b32_e32 v71, v41
	v_pk_fma_f32 v[62:63], v[62:63], v[62:63], v[68:69]
	v_mov_b32_e32 v68, v43
	v_mov_b32_e32 v69, v47
	v_mov_b32_e32 v66, v29
	v_mov_b32_e32 v67, v33
	v_pk_fma_f32 v[60:61], v[64:65], v[64:65], v[60:61]
	v_mov_b32_e32 v64, v42
	v_mov_b32_e32 v65, v46
	v_pk_mul_f32 v[68:69], v[68:69], v[68:69]
	v_pk_fma_f32 v[62:63], v[70:71], v[70:71], v[62:63]
	v_mov_b32_e32 v70, v51
	v_mov_b32_e32 v71, v55
	v_pk_fma_f32 v[60:61], v[66:67], v[66:67], v[60:61]
	v_mov_b32_e32 v66, v44
	v_mov_b32_e32 v67, v48
	v_pk_fma_f32 v[64:65], v[64:65], v[64:65], v[68:69]
	v_mov_b32_e32 v68, v50
	v_mov_b32_e32 v69, v54
	v_pk_mul_f32 v[70:71], v[70:71], v[70:71]
	v_pk_fma_f32 v[64:65], v[66:67], v[66:67], v[64:65]
	v_pk_fma_f32 v[68:69], v[68:69], v[68:69], v[70:71]
	v_mov_b32_e32 v70, v45
	v_mov_b32_e32 v71, v49
	v_mov_b32_e32 v66, v52
	v_mov_b32_e32 v67, v56
	v_pk_fma_f32 v[66:67], v[66:67], v[66:67], v[68:69]
	v_mov_b32_e32 v68, v53
	v_mov_b32_e32 v69, v57
	v_pk_fma_f32 v[64:65], v[70:71], v[70:71], v[64:65]
	v_mov_b32_e32 v71, v60
	v_pk_fma_f32 v[66:67], v[68:69], v[68:69], v[66:67]
	v_mov_b32_e32 v70, v64
	v_mov_b32_e32 v60, v65
	v_mov_b32_e32 v69, v62
	v_mov_b32_e32 v68, v66
	v_pk_add_f32 v[60:61], v[70:71], v[60:61]
	v_mov_b32_e32 v62, v67
	v_pk_add_f32 v[60:61], v[60:61], v[68:69]
	s_nop 0
	v_pk_add_f32 v[60:61], v[60:61], v[62:63]
	ds_swizzle_b32 v63, v61 offset:swizzle(SWAP,16)
	ds_swizzle_b32 v62, v60 offset:swizzle(SWAP,16)
	s_waitcnt lgkmcnt(0)
	v_pk_add_f32 v[60:61], v[60:61], v[62:63]
	ds_swizzle_b32 v63, v61 offset:swizzle(SWAP,8)
	ds_swizzle_b32 v62, v60 offset:swizzle(SWAP,8)
	s_waitcnt lgkmcnt(0)
	v_pk_add_f32 v[60:61], v[60:61], v[62:63]
	ds_swizzle_b32 v63, v61 offset:swizzle(SWAP,4)
	ds_swizzle_b32 v62, v60 offset:swizzle(SWAP,4)
	s_waitcnt lgkmcnt(0)
	v_pk_add_f32 v[60:61], v[60:61], v[62:63]
	ds_swizzle_b32 v63, v61 offset:swizzle(SWAP,2)
	ds_swizzle_b32 v62, v60 offset:swizzle(SWAP,2)
	s_waitcnt lgkmcnt(0)
	v_pk_add_f32 v[60:61], v[60:61], v[62:63]
	ds_swizzle_b32 v63, v61 offset:swizzle(SWAP,1)
	ds_swizzle_b32 v62, v60 offset:swizzle(SWAP,1)
	s_waitcnt lgkmcnt(0)
	v_pk_add_f32 v[60:61], v[60:61], v[62:63]
	ds_bpermute_b32 v63, v0, v61
	ds_bpermute_b32 v62, v23, v60
	s_waitcnt lgkmcnt(0)
	v_pk_add_f32 v[60:61], v[60:61], v[62:63]
	s_nop 0
	v_pk_fma_f32 v[60:61], v[60:61], s[58:59], v[154:155] op_sel_hi:[1,0,0]
	s_nop 0
	v_mul_f32_e32 v0, 0x4b800000, v61
	v_cmp_gt_f32_e64 s[2:3], s46, v61
	v_mul_f32_e32 v23, 0x4b800000, v60
	v_cmp_gt_f32_e32 vcc, s46, v60
	v_cndmask_b32_e64 v0, v61, v0, s[2:3]
	v_rsq_f32_e32 v0, v0
	v_cndmask_b32_e32 v23, v60, v23, vcc
	v_rsq_f32_e32 v23, v23
	v_mul_f32_e32 v60, 0x45800000, v0
	v_cndmask_b32_e64 v0, v0, v60, s[2:3]
	v_mul_f32_e32 v61, 0x45800000, v23
	v_cndmask_b32_e32 v60, v23, v61, vcc
	v_pk_mul_f32 v[26:27], v[26:27], v[0:1] op_sel_hi:[1,0]
	v_pk_mul_f32 v[28:29], v[28:29], v[0:1] op_sel_hi:[1,0]
	v_pk_mul_f32 v[30:31], v[30:31], v[0:1] op_sel_hi:[1,0]
	v_pk_mul_f32 v[32:33], v[32:33], v[0:1] op_sel_hi:[1,0]
	v_pk_mul_f32 v[42:43], v[42:43], v[60:61] op_sel_hi:[1,0]
	v_pk_mul_f32 v[44:45], v[44:45], v[60:61] op_sel_hi:[1,0]
	v_pk_mul_f32 v[46:47], v[46:47], v[60:61] op_sel_hi:[1,0]
	v_pk_mul_f32 v[48:49], v[48:49], v[60:61] op_sel_hi:[1,0]
	v_pk_mul_f32 v[34:35], v[34:35], v[0:1] op_sel_hi:[1,0]
	v_pk_mul_f32 v[36:37], v[36:37], v[0:1] op_sel_hi:[1,0]
	v_pk_mul_f32 v[38:39], v[38:39], v[0:1] op_sel_hi:[1,0]
	v_pk_mul_f32 v[40:41], v[40:41], v[0:1] op_sel_hi:[1,0]
	v_pk_mul_f32 v[50:51], v[50:51], v[60:61] op_sel_hi:[1,0]
	v_pk_mul_f32 v[52:53], v[52:53], v[60:61] op_sel_hi:[1,0]
	v_pk_mul_f32 v[54:55], v[54:55], v[60:61] op_sel_hi:[1,0]
	v_pk_mul_f32 v[56:57], v[56:57], v[60:61] op_sel_hi:[1,0]
	v_pk_mul_f32 v[28:29], v[8:9], v[28:29]
	v_pk_mul_f32 v[26:27], v[6:7], v[26:27]
	v_pk_mul_f32 v[32:33], v[4:5], v[32:33]
	v_pk_mul_f32 v[30:31], v[2:3], v[30:31]
	v_pk_mul_f32 v[44:45], v[8:9], v[44:45]
	v_pk_mul_f32 v[42:43], v[6:7], v[42:43]
	v_pk_mul_f32 v[48:49], v[4:5], v[48:49]
	v_pk_mul_f32 v[46:47], v[2:3], v[46:47]
	v_pk_mul_f32 v[36:37], v[16:17], v[36:37]
	v_pk_mul_f32 v[34:35], v[14:15], v[34:35]
	v_pk_mul_f32 v[40:41], v[12:13], v[40:41]
	v_pk_mul_f32 v[38:39], v[10:11], v[38:39]
	v_pk_mul_f32 v[52:53], v[16:17], v[52:53]
	v_pk_mul_f32 v[50:51], v[14:15], v[50:51]
	v_pk_mul_f32 v[56:57], v[12:13], v[56:57]
	v_pk_mul_f32 v[54:55], v[10:11], v[54:55]
	v_cvt_pk_bf16_f32 v26, v26, v27
	v_cvt_pk_bf16_f32 v27, v28, v29
	v_cvt_pk_bf16_f32 v28, v30, v31
	v_cvt_pk_bf16_f32 v29, v32, v33
	v_cvt_pk_bf16_f32 v30, v42, v43
	v_cvt_pk_bf16_f32 v31, v44, v45
	v_cvt_pk_bf16_f32 v32, v46, v47
	v_cvt_pk_bf16_f32 v33, v48, v49
	v_cvt_pk_bf16_f32 v34, v34, v35
	v_cvt_pk_bf16_f32 v35, v36, v37
	v_cvt_pk_bf16_f32 v36, v38, v39
	v_cvt_pk_bf16_f32 v37, v40, v41
	v_cvt_pk_bf16_f32 v38, v50, v51
	v_cvt_pk_bf16_f32 v39, v52, v53
	v_cvt_pk_bf16_f32 v40, v54, v55
	v_cvt_pk_bf16_f32 v41, v56, v57
	global_store_dwordx4 v[24:25], v[26:29], off
	global_store_dwordx4 v[58:59], v[30:33], off
	global_store_dwordx4 v[24:25], v[34:37], off offset:1024
	global_store_dwordx4 v[58:59], v[38:41], off offset:1024
	s_branch .Ln1_loop
; __device__ __forceinline__ void store8bf(bf16_t* p, f32x4 v0, f32x4 v1) { u32x4 w; w.x = cvt_pk_bf16(v0[0], v0[1]); w.y = cvt_pk_bf16(v0[2], v0[3]); w.z = cvt_pk_bf16(v1[0], v1[1]); w.w = cvt_pk_bf16(v1[2], v1[3]); *(u32x4*)p = w; }
; __device__ __forceinline__ void norm_phase(const float* H, const float* g, bf16_t* HN) {
;     ...
;     const float* p = H + (size_t)row * DM + lane * 8; const float* p2 = H + (size_t)row2 * DM + lane * 8; f32x4 v[4], u[4]; float ss = 0.f, ss2 = 0.f;
; #pragma unroll
;     for (int i = 0; i < 4; ++i) { v[i] = *(const f32x4*)(p + 512 * (i >> 1) + 4 * (i & 1)); u[i] = *(const f32x4*)(p2 + 512 * (i >> 1) + 4 * (i & 1)); }
; #pragma unroll
;     for (int i = 0; i < 4; ++i) { ss += v[i][0] * v[i][0] + v[i][1] * v[i][1] + v[i][2] * v[i][2] + v[i][3] * v[i][3]; ss2 += u[i][0] * u[i][0] + u[i][1] * u[i][1] + u[i][2] * u[i][2] + u[i][3] * u[i][3]; }
;     ss = wave_sum(ss); ss2 = wave_sum(ss2); const float rs = rsqrtf(ss * (1.0f / 1024.0f) + 1e-6f), rs2 = rsqrtf(ss2 * (1.0f / 1024.0f) + 1e-6f);
;     bf16_t* q = HN + (size_t)row * DM + lane * 8; bf16_t* q2 = HN + (size_t)row2 * DM + lane * 8;
; #pragma unroll
;     for (int i = 0; i < 2; ++i) { store8bf(q + 512 * i, v[2 * i] * rs * gv[2 * i], v[2 * i + 1] * rs * gv[2 * i + 1]); store8bf(q2 + 512 * i, u[2 * i] * rs2 * gv[2 * i], u[2 * i + 1] * rs2 * gv[2 * i + 1]); }
.Ln1_lastA_first:
	s_waitcnt vmcnt(0)
	v_lshlrev_b32_e32 v0, 2, v210
	v_xor_b32_e32 v0, 0x80, v0
	v_mov_b32_e32 v23, v0
	v_mov_b32_e32 v62, v27
	v_mov_b32_e32 v63, v31
	v_mov_b32_e32 v70, v35
	v_mov_b32_e32 v71, v39
	v_mov_b32_e32 v60, v26
	v_mov_b32_e32 v61, v30
	v_mov_b32_e32 v68, v34
	v_mov_b32_e32 v69, v38
	v_pk_mul_f32 v[62:63], v[62:63], v[62:63]
	v_pk_mul_f32 v[70:71], v[70:71], v[70:71]
	v_pk_fma_f32 v[60:61], v[60:61], v[60:61], v[62:63]
	v_mov_b32_e32 v62, v36
	v_mov_b32_e32 v63, v40
	v_pk_fma_f32 v[68:69], v[68:69], v[68:69], v[70:71]
	v_mov_b32_e32 v64, v28
	v_mov_b32_e32 v65, v32
	v_mov_b32_e32 v70, v37
	v_mov_b32_e32 v71, v41
	v_pk_fma_f32 v[62:63], v[62:63], v[62:63], v[68:69]
	v_mov_b32_e32 v68, v43
	v_mov_b32_e32 v69, v47
	v_mov_b32_e32 v66, v29
	v_mov_b32_e32 v67, v33
	v_pk_fma_f32 v[60:61], v[64:65], v[64:65], v[60:61]
	v_mov_b32_e32 v64, v42
	v_mov_b32_e32 v65, v46
	v_pk_mul_f32 v[68:69], v[68:69], v[68:69]
	v_pk_fma_f32 v[62:63], v[70:71], v[70:71], v[62:63]
	v_mov_b32_e32 v70, v51
	v_mov_b32_e32 v71, v55
	v_pk_fma_f32 v[60:61], v[66:67], v[66:67], v[60:61]
	v_mov_b32_e32 v66, v44
	v_mov_b32_e32 v67, v48
	v_pk_fma_f32 v[64:65], v[64:65], v[64:65], v[68:69]
	v_mov_b32_e32 v68, v50
	v_mov_b32_e32 v69, v54
	v_pk_mul_f32 v[70:71], v[70:71], v[70:71]
	v_pk_fma_f32 v[64:65], v[66:67], v[66:67], v[64:65]
	v_pk_fma_f32 v[68:69], v[68:69], v[68:69], v[70:71]
	v_mov_b32_e32 v70, v45
	v_mov_b32_e32 v71, v49
	v_mov_b32_e32 v66, v52
	v_mov_b32_e32 v67, v56
	v_pk_fma_f32 v[66:67], v[66:67], v[66:67], v[68:69]
	v_mov_b32_e32 v68, v53
	v_mov_b32_e32 v69, v57
	v_pk_fma_f32 v[64:65], v[70:71], v[70:71], v[64:65]
	v_mov_b32_e32 v71, v60
	v_pk_fma_f32 v[66:67], v[68:69], v[68:69], v[66:67]
	v_mov_b32_e32 v70, v64
	v_mov_b32_e32 v60, v65
	v_mov_b32_e32 v69, v62
	v_mov_b32_e32 v68, v66
	v_pk_add_f32 v[60:61], v[70:71], v[60:61]
	v_mov_b32_e32 v62, v67
	v_pk_add_f32 v[60:61], v[60:61], v[68:69]
	s_nop 0
	v_pk_add_f32 v[60:61], v[60:61], v[62:63]
	ds_swizzle_b32 v63, v61 offset:swizzle(SWAP,16)
	ds_swizzle_b32 v62, v60 offset:swizzle(SWAP,16)
	s_waitcnt lgkmcnt(0)
	v_pk_add_f32 v[60:61], v[60:61], v[62:63]
	ds_swizzle_b32 v63, v61 offset:swizzle(SWAP,8)
	ds_swizzle_b32 v62, v60 offset:swizzle(SWAP,8)
	s_waitcnt lgkmcnt(0)
	v_pk_add_f32 v[60:61], v[60:61], v[62:63]
	ds_swizzle_b32 v63, v61 offset:swizzle(SWAP,4)
	ds_swizzle_b32 v62, v60 offset:swizzle(SWAP,4)
	s_waitcnt lgkmcnt(0)
	v_pk_add_f32 v[60:61], v[60:61], v[62:63]
	ds_swizzle_b32 v63, v61 offset:swizzle(SWAP,2)
	ds_swizzle_b32 v62, v60 offset:swizzle(SWAP,2)
	s_waitcnt lgkmcnt(0)
	v_pk_add_f32 v[60:61], v[60:61], v[62:63]
	ds_swizzle_b32 v63, v61 offset:swizzle(SWAP,1)
	ds_swizzle_b32 v62, v60 offset:swizzle(SWAP,1)
	s_waitcnt lgkmcnt(0)
	v_pk_add_f32 v[60:61], v[60:61], v[62:63]
	ds_bpermute_b32 v63, v0, v61
	ds_bpermute_b32 v62, v23, v60
	s_waitcnt lgkmcnt(0)
	v_pk_add_f32 v[60:61], v[60:61], v[62:63]
	s_nop 0
	v_pk_fma_f32 v[60:61], v[60:61], s[58:59], v[154:155] op_sel_hi:[1,0,0]
	s_nop 0
	v_mul_f32_e32 v0, 0x4b800000, v61
	v_cmp_gt_f32_e64 s[2:3], s46, v61
	v_mul_f32_e32 v23, 0x4b800000, v60
	v_cmp_gt_f32_e32 vcc, s46, v60
	v_cndmask_b32_e64 v0, v61, v0, s[2:3]
	v_rsq_f32_e32 v0, v0
	v_cndmask_b32_e32 v23, v60, v23, vcc
	v_rsq_f32_e32 v23, v23
	v_mul_f32_e32 v60, 0x45800000, v0
	v_cndmask_b32_e64 v0, v0, v60, s[2:3]
	v_mul_f32_e32 v61, 0x45800000, v23
	v_cndmask_b32_e32 v60, v23, v61, vcc
	v_pk_mul_f32 v[26:27], v[26:27], v[0:1] op_sel_hi:[1,0]
	v_pk_mul_f32 v[28:29], v[28:29], v[0:1] op_sel_hi:[1,0]
	v_pk_mul_f32 v[30:31], v[30:31], v[0:1] op_sel_hi:[1,0]
	v_pk_mul_f32 v[32:33], v[32:33], v[0:1] op_sel_hi:[1,0]
	v_pk_mul_f32 v[42:43], v[42:43], v[60:61] op_sel_hi:[1,0]
	v_pk_mul_f32 v[44:45], v[44:45], v[60:61] op_sel_hi:[1,0]
	v_pk_mul_f32 v[46:47], v[46:47], v[60:61] op_sel_hi:[1,0]
	v_pk_mul_f32 v[48:49], v[48:49], v[60:61] op_sel_hi:[1,0]
	v_pk_mul_f32 v[34:35], v[34:35], v[0:1] op_sel_hi:[1,0]
	v_pk_mul_f32 v[36:37], v[36:37], v[0:1] op_sel_hi:[1,0]
	v_pk_mul_f32 v[38:39], v[38:39], v[0:1] op_sel_hi:[1,0]
	v_pk_mul_f32 v[40:41], v[40:41], v[0:1] op_sel_hi:[1,0]
	v_pk_mul_f32 v[50:51], v[50:51], v[60:61] op_sel_hi:[1,0]
	v_pk_mul_f32 v[52:53], v[52:53], v[60:61] op_sel_hi:[1,0]
	v_pk_mul_f32 v[54:55], v[54:55], v[60:61] op_sel_hi:[1,0]
	v_pk_mul_f32 v[56:57], v[56:57], v[60:61] op_sel_hi:[1,0]
	v_pk_mul_f32 v[28:29], v[8:9], v[28:29]
	v_pk_mul_f32 v[26:27], v[6:7], v[26:27]
	v_pk_mul_f32 v[32:33], v[4:5], v[32:33]
	v_pk_mul_f32 v[30:31], v[2:3], v[30:31]
	v_pk_mul_f32 v[44:45], v[8:9], v[44:45]
	v_pk_mul_f32 v[42:43], v[6:7], v[42:43]
	v_pk_mul_f32 v[48:49], v[4:5], v[48:49]
	v_pk_mul_f32 v[46:47], v[2:3], v[46:47]
	v_pk_mul_f32 v[36:37], v[16:17], v[36:37]
	v_pk_mul_f32 v[34:35], v[14:15], v[34:35]
	v_pk_mul_f32 v[40:41], v[12:13], v[40:41]
	v_pk_mul_f32 v[38:39], v[10:11], v[38:39]
	v_pk_mul_f32 v[52:53], v[16:17], v[52:53]
	v_pk_mul_f32 v[50:51], v[14:15], v[50:51]
	v_pk_mul_f32 v[56:57], v[12:13], v[56:57]
	v_pk_mul_f32 v[54:55], v[10:11], v[54:55]
	v_cvt_pk_bf16_f32 v26, v26, v27
	v_cvt_pk_bf16_f32 v27, v28, v29
	v_cvt_pk_bf16_f32 v28, v30, v31
	v_cvt_pk_bf16_f32 v29, v32, v33
	v_cvt_pk_bf16_f32 v30, v42, v43
	v_cvt_pk_bf16_f32 v31, v44, v45
	v_cvt_pk_bf16_f32 v32, v46, v47
	v_cvt_pk_bf16_f32 v33, v48, v49
	v_cvt_pk_bf16_f32 v34, v34, v35
	v_cvt_pk_bf16_f32 v35, v36, v37
	v_cvt_pk_bf16_f32 v36, v38, v39
	v_cvt_pk_bf16_f32 v37, v40, v41
	v_cvt_pk_bf16_f32 v38, v50, v51
	v_cvt_pk_bf16_f32 v39, v52, v53
	v_cvt_pk_bf16_f32 v40, v54, v55
	v_cvt_pk_bf16_f32 v41, v56, v57
	global_store_dwordx4 v[24:25], v[26:29], off
	global_store_dwordx4 v[58:59], v[30:33], off
	global_store_dwordx4 v[24:25], v[34:37], off offset:1024
	global_store_dwordx4 v[58:59], v[38:41], off offset:1024
	s_branch .Ln1_done
; __device__ __forceinline__ void store8bf(bf16_t* p, f32x4 v0, f32x4 v1) { u32x4 w; w.x = cvt_pk_bf16(v0[0], v0[1]); w.y = cvt_pk_bf16(v0[2], v0[3]); w.z = cvt_pk_bf16(v1[0], v1[1]); w.w = cvt_pk_bf16(v1[2], v1[3]); *(u32x4*)p = w; }
; __device__ __forceinline__ void norm_phase(const float* H, const float* g, bf16_t* HN) {
;     ...
;     const float* p = H + (size_t)row * DM + lane * 8; const float* p2 = H + (size_t)row2 * DM + lane * 8; f32x4 v[4], u[4]; float ss = 0.f, ss2 = 0.f;
; #pragma unroll
;     for (int i = 0; i < 4; ++i) { v[i] = *(const f32x4*)(p + 512 * (i >> 1) + 4 * (i & 1)); u[i] = *(const f32x4*)(p2 + 512 * (i >> 1) + 4 * (i & 1)); }
; #pragma unroll
;     for (int i = 0; i < 4; ++i) { ss += v[i][0] * v[i][0] + v[i][1] * v[i][1] + v[i][2] * v[i][2] + v[i][3] * v[i][3]; ss2 += u[i][0] * u[i][0] + u[i][1] * u[i][1] + u[i][2] * u[i][2] + u[i][3] * u[i][3]; }
;     ss = wave_sum(ss); ss2 = wave_sum(ss2); const float rs = rsqrtf(ss * (1.0f / 1024.0f) + 1e-6f), rs2 = rsqrtf(ss2 * (1.0f / 1024.0f) + 1e-6f);
;     bf16_t* q = HN + (size_t)row * DM + lane * 8; bf16_t* q2 = HN + (size_t)row2 * DM + lane * 8;
; #pragma unroll
;     for (int i = 0; i < 2; ++i) { store8bf(q + 512 * i, v[2 * i] * rs * gv[2 * i], v[2 * i + 1] * rs * gv[2 * i + 1]); store8bf(q2 + 512 * i, u[2 * i] * rs2 * gv[2 * i], u[2 * i + 1] * rs2 * gv[2 * i + 1]); }
.Ln1_lastB:
	s_waitcnt vmcnt(0)
	v_lshlrev_b32_e32 v0, 2, v210
	v_xor_b32_e32 v0, 0x80, v0
	v_mov_b32_e32 v23, v0
	v_mov_b32_e32 v62, v73
	v_mov_b32_e32 v63, v77
	v_mov_b32_e32 v70, v81
	v_mov_b32_e32 v71, v89
	v_mov_b32_e32 v60, v72
	v_mov_b32_e32 v61, v76
	v_mov_b32_e32 v68, v80
	v_mov_b32_e32 v69, v88
	v_pk_mul_f32 v[62:63], v[62:63], v[62:63]
	v_pk_mul_f32 v[70:71], v[70:71], v[70:71]
	v_pk_fma_f32 v[60:61], v[60:61], v[60:61], v[62:63]
	v_mov_b32_e32 v62, v82
	v_mov_b32_e32 v63, v90
	v_pk_fma_f32 v[68:69], v[68:69], v[68:69], v[70:71]
	v_mov_b32_e32 v64, v74
	v_mov_b32_e32 v65, v78
	v_mov_b32_e32 v70, v83
	v_mov_b32_e32 v71, v91
	v_pk_fma_f32 v[62:63], v[62:63], v[62:63], v[68:69]
	v_mov_b32_e32 v68, v93
	v_mov_b32_e32 v69, v97
	v_mov_b32_e32 v66, v75
	v_mov_b32_e32 v67, v79
	v_pk_fma_f32 v[60:61], v[64:65], v[64:65], v[60:61]
	v_mov_b32_e32 v64, v92
	v_mov_b32_e32 v65, v96
	v_pk_mul_f32 v[68:69], v[68:69], v[68:69]
	v_pk_fma_f32 v[62:63], v[70:71], v[70:71], v[62:63]
	v_mov_b32_e32 v70, v101
	v_mov_b32_e32 v71, v129
	v_pk_fma_f32 v[60:61], v[66:67], v[66:67], v[60:61]
	v_mov_b32_e32 v66, v94
	v_mov_b32_e32 v67, v98
	v_pk_fma_f32 v[64:65], v[64:65], v[64:65], v[68:69]
	v_mov_b32_e32 v68, v100
	v_mov_b32_e32 v69, v128
	v_pk_mul_f32 v[70:71], v[70:71], v[70:71]
	v_pk_fma_f32 v[64:65], v[66:67], v[66:67], v[64:65]
	v_pk_fma_f32 v[68:69], v[68:69], v[68:69], v[70:71]
	v_mov_b32_e32 v70, v95
	v_mov_b32_e32 v71, v99
	v_mov_b32_e32 v66, v102
	v_mov_b32_e32 v67, v130
	v_pk_fma_f32 v[66:67], v[66:67], v[66:67], v[68:69]
	v_mov_b32_e32 v68, v103
	v_mov_b32_e32 v69, v131
	v_pk_fma_f32 v[64:65], v[70:71], v[70:71], v[64:65]
	v_mov_b32_e32 v71, v60
	v_pk_fma_f32 v[66:67], v[68:69], v[68:69], v[66:67]
	v_mov_b32_e32 v70, v64
	v_mov_b32_e32 v60, v65
	v_mov_b32_e32 v69, v62
	v_mov_b32_e32 v68, v66
	v_pk_add_f32 v[60:61], v[70:71], v[60:61]
	v_mov_b32_e32 v62, v67
	v_pk_add_f32 v[60:61], v[60:61], v[68:69]
	s_nop 0
	v_pk_add_f32 v[60:61], v[60:61], v[62:63]
	ds_swizzle_b32 v63, v61 offset:swizzle(SWAP,16)
	ds_swizzle_b32 v62, v60 offset:swizzle(SWAP,16)
	s_waitcnt lgkmcnt(0)
	v_pk_add_f32 v[60:61], v[60:61], v[62:63]
	ds_swizzle_b32 v63, v61 offset:swizzle(SWAP,8)
	ds_swizzle_b32 v62, v60 offset:swizzle(SWAP,8)
	s_waitcnt lgkmcnt(0)
	v_pk_add_f32 v[60:61], v[60:61], v[62:63]
	ds_swizzle_b32 v63, v61 offset:swizzle(SWAP,4)
	ds_swizzle_b32 v62, v60 offset:swizzle(SWAP,4)
	s_waitcnt lgkmcnt(0)
	v_pk_add_f32 v[60:61], v[60:61], v[62:63]
	ds_swizzle_b32 v63, v61 offset:swizzle(SWAP,2)
	ds_swizzle_b32 v62, v60 offset:swizzle(SWAP,2)
	s_waitcnt lgkmcnt(0)
	v_pk_add_f32 v[60:61], v[60:61], v[62:63]
	ds_swizzle_b32 v63, v61 offset:swizzle(SWAP,1)
	ds_swizzle_b32 v62, v60 offset:swizzle(SWAP,1)
	s_waitcnt lgkmcnt(0)
	v_pk_add_f32 v[60:61], v[60:61], v[62:63]
	ds_bpermute_b32 v63, v0, v61
	ds_bpermute_b32 v62, v23, v60
	s_waitcnt lgkmcnt(0)
	v_pk_add_f32 v[60:61], v[60:61], v[62:63]
	s_nop 0
	v_pk_fma_f32 v[60:61], v[60:61], s[58:59], v[154:155] op_sel_hi:[1,0,0]
	s_nop 0
	v_mul_f32_e32 v0, 0x4b800000, v61
	v_cmp_gt_f32_e64 s[2:3], s46, v61
	v_mul_f32_e32 v23, 0x4b800000, v60
	v_cmp_gt_f32_e32 vcc, s46, v60
	v_cndmask_b32_e64 v0, v61, v0, s[2:3]
	v_rsq_f32_e32 v0, v0
	v_cndmask_b32_e32 v23, v60, v23, vcc
	v_rsq_f32_e32 v23, v23
	v_mul_f32_e32 v60, 0x45800000, v0
	v_cndmask_b32_e64 v0, v0, v60, s[2:3]
	v_mul_f32_e32 v61, 0x45800000, v23
	v_cndmask_b32_e32 v60, v23, v61, vcc
	v_pk_mul_f32 v[72:73], v[72:73], v[0:1] op_sel_hi:[1,0]
	v_pk_mul_f32 v[74:75], v[74:75], v[0:1] op_sel_hi:[1,0]
	v_pk_mul_f32 v[76:77], v[76:77], v[0:1] op_sel_hi:[1,0]
	v_pk_mul_f32 v[78:79], v[78:79], v[0:1] op_sel_hi:[1,0]
	v_pk_mul_f32 v[92:93], v[92:93], v[60:61] op_sel_hi:[1,0]
	v_pk_mul_f32 v[94:95], v[94:95], v[60:61] op_sel_hi:[1,0]
	v_pk_mul_f32 v[96:97], v[96:97], v[60:61] op_sel_hi:[1,0]
	v_pk_mul_f32 v[98:99], v[98:99], v[60:61] op_sel_hi:[1,0]
	v_pk_mul_f32 v[80:81], v[80:81], v[0:1] op_sel_hi:[1,0]
	v_pk_mul_f32 v[82:83], v[82:83], v[0:1] op_sel_hi:[1,0]
	v_pk_mul_f32 v[88:89], v[88:89], v[0:1] op_sel_hi:[1,0]
	v_pk_mul_f32 v[90:91], v[90:91], v[0:1] op_sel_hi:[1,0]
	v_pk_mul_f32 v[100:101], v[100:101], v[60:61] op_sel_hi:[1,0]
	v_pk_mul_f32 v[102:103], v[102:103], v[60:61] op_sel_hi:[1,0]
	v_pk_mul_f32 v[128:129], v[128:129], v[60:61] op_sel_hi:[1,0]
	v_pk_mul_f32 v[130:131], v[130:131], v[60:61] op_sel_hi:[1,0]
	v_pk_mul_f32 v[74:75], v[8:9], v[74:75]
	v_pk_mul_f32 v[72:73], v[6:7], v[72:73]
	v_pk_mul_f32 v[78:79], v[4:5], v[78:79]
	v_pk_mul_f32 v[76:77], v[2:3], v[76:77]
	v_pk_mul_f32 v[94:95], v[8:9], v[94:95]
	v_pk_mul_f32 v[92:93], v[6:7], v[92:93]
	v_pk_mul_f32 v[98:99], v[4:5], v[98:99]
	v_pk_mul_f32 v[96:97], v[2:3], v[96:97]
	v_pk_mul_f32 v[82:83], v[16:17], v[82:83]
	v_pk_mul_f32 v[80:81], v[14:15], v[80:81]
	v_pk_mul_f32 v[90:91], v[12:13], v[90:91]
	v_pk_mul_f32 v[88:89], v[10:11], v[88:89]
	v_pk_mul_f32 v[102:103], v[16:17], v[102:103]
	v_pk_mul_f32 v[100:101], v[14:15], v[100:101]
	v_pk_mul_f32 v[130:131], v[12:13], v[130:131]
	v_pk_mul_f32 v[128:129], v[10:11], v[128:129]
	v_cvt_pk_bf16_f32 v72, v72, v73
	v_cvt_pk_bf16_f32 v73, v74, v75
	v_cvt_pk_bf16_f32 v74, v76, v77
	v_cvt_pk_bf16_f32 v75, v78, v79
	v_cvt_pk_bf16_f32 v76, v92, v93
	v_cvt_pk_bf16_f32 v77, v94, v95
	v_cvt_pk_bf16_f32 v78, v96, v97
	v_cvt_pk_bf16_f32 v79, v98, v99
	v_cvt_pk_bf16_f32 v80, v80, v81
	v_cvt_pk_bf16_f32 v81, v82, v83
	v_cvt_pk_bf16_f32 v82, v88, v89
	v_cvt_pk_bf16_f32 v83, v90, v91
	v_cvt_pk_bf16_f32 v88, v100, v101
	v_cvt_pk_bf16_f32 v89, v102, v103
	v_cvt_pk_bf16_f32 v90, v128, v129
	v_cvt_pk_bf16_f32 v91, v130, v131
	global_store_dwordx4 v[132:133], v[72:75], off
	global_store_dwordx4 v[134:135], v[76:79], off
	global_store_dwordx4 v[132:133], v[80:83], off offset:1024
	global_store_dwordx4 v[134:135], v[88:91], off offset:1024
	s_branch .Ln1_done
; __device__ __forceinline__ void store8bf(bf16_t* p, f32x4 v0, f32x4 v1) { u32x4 w; w.x = cvt_pk_bf16(v0[0], v0[1]); w.y = cvt_pk_bf16(v0[2], v0[3]); w.z = cvt_pk_bf16(v1[0], v1[1]); w.w = cvt_pk_bf16(v1[2], v1[3]); *(u32x4*)p = w; }
; __device__ __forceinline__ void norm_phase(const float* H, const float* g, bf16_t* HN) {
;     ...
;     const float* p = H + (size_t)row * DM + lane * 8; const float* p2 = H + (size_t)row2 * DM + lane * 8; f32x4 v[4], u[4]; float ss = 0.f, ss2 = 0.f;
; #pragma unroll
;     for (int i = 0; i < 4; ++i) { v[i] = *(const f32x4*)(p + 512 * (i >> 1) + 4 * (i & 1)); u[i] = *(const f32x4*)(p2 + 512 * (i >> 1) + 4 * (i & 1)); }
; #pragma unroll
;     for (int i = 0; i < 4; ++i) { ss += v[i][0] * v[i][0] + v[i][1] * v[i][1] + v[i][2] * v[i][2] + v[i][3] * v[i][3]; ss2 += u[i][0] * u[i][0] + u[i][1] * u[i][1] + u[i][2] * u[i][2] + u[i][3] * u[i][3]; }
;     ss = wave_sum(ss); ss2 = wave_sum(ss2); const float rs = rsqrtf(ss * (1.0f / 1024.0f) + 1e-6f), rs2 = rsqrtf(ss2 * (1.0f / 1024.0f) + 1e-6f);
;     bf16_t* q = HN + (size_t)row * DM + lane * 8; bf16_t* q2 = HN + (size_t)row2 * DM + lane * 8;
; #pragma unroll
;     for (int i = 0; i < 2; ++i) { store8bf(q + 512 * i, v[2 * i] * rs * gv[2 * i], v[2 * i + 1] * rs * gv[2 * i + 1]); store8bf(q2 + 512 * i, u[2 * i] * rs2 * gv[2 * i], u[2 * i + 1] * rs2 * gv[2 * i + 1]); }
.Ln1_lastA:
	s_waitcnt vmcnt(0)
	v_lshlrev_b32_e32 v0, 2, v210
	v_xor_b32_e32 v0, 0x80, v0
	v_mov_b32_e32 v23, v0
	v_mov_b32_e32 v62, v27
	v_mov_b32_e32 v63, v31
	v_mov_b32_e32 v70, v35
	v_mov_b32_e32 v71, v39
	v_mov_b32_e32 v60, v26
	v_mov_b32_e32 v61, v30
	v_mov_b32_e32 v68, v34
	v_mov_b32_e32 v69, v38
	v_pk_mul_f32 v[62:63], v[62:63], v[62:63]
	v_pk_mul_f32 v[70:71], v[70:71], v[70:71]
	v_pk_fma_f32 v[60:61], v[60:61], v[60:61], v[62:63]
	v_mov_b32_e32 v62, v36
	v_mov_b32_e32 v63, v40
	v_pk_fma_f32 v[68:69], v[68:69], v[68:69], v[70:71]
	v_mov_b32_e32 v64, v28
	v_mov_b32_e32 v65, v32
	v_mov_b32_e32 v70, v37
	v_mov_b32_e32 v71, v41
	v_pk_fma_f32 v[62:63], v[62:63], v[62:63], v[68:69]
	v_mov_b32_e32 v68, v43
	v_mov_b32_e32 v69, v47
	v_mov_b32_e32 v66, v29
	v_mov_b32_e32 v67, v33
	v_pk_fma_f32 v[60:61], v[64:65], v[64:65], v[60:61]
	v_mov_b32_e32 v64, v42
	v_mov_b32_e32 v65, v46
	v_pk_mul_f32 v[68:69], v[68:69], v[68:69]
	v_pk_fma_f32 v[62:63], v[70:71], v[70:71], v[62:63]
	v_mov_b32_e32 v70, v51
	v_mov_b32_e32 v71, v55
	v_pk_fma_f32 v[60:61], v[66:67], v[66:67], v[60:61]
	v_mov_b32_e32 v66, v44
	v_mov_b32_e32 v67, v48
	v_pk_fma_f32 v[64:65], v[64:65], v[64:65], v[68:69]
	v_mov_b32_e32 v68, v50
	v_mov_b32_e32 v69, v54
	v_pk_mul_f32 v[70:71], v[70:71], v[70:71]
	v_pk_fma_f32 v[64:65], v[66:67], v[66:67], v[64:65]
	v_pk_fma_f32 v[68:69], v[68:69], v[68:69], v[70:71]
	v_mov_b32_e32 v70, v45
	v_mov_b32_e32 v71, v49
	v_mov_b32_e32 v66, v52
	v_mov_b32_e32 v67, v56
	v_pk_fma_f32 v[66:67], v[66:67], v[66:67], v[68:69]
	v_mov_b32_e32 v68, v53
	v_mov_b32_e32 v69, v57
	v_pk_fma_f32 v[64:65], v[70:71], v[70:71], v[64:65]
	v_mov_b32_e32 v71, v60
	v_pk_fma_f32 v[66:67], v[68:69], v[68:69], v[66:67]
	v_mov_b32_e32 v70, v64
	v_mov_b32_e32 v60, v65
	v_mov_b32_e32 v69, v62
	v_mov_b32_e32 v68, v66
	v_pk_add_f32 v[60:61], v[70:71], v[60:61]
	v_mov_b32_e32 v62, v67
	v_pk_add_f32 v[60:61], v[60:61], v[68:69]
	s_nop 0
	v_pk_add_f32 v[60:61], v[60:61], v[62:63]
	ds_swizzle_b32 v63, v61 offset:swizzle(SWAP,16)
	ds_swizzle_b32 v62, v60 offset:swizzle(SWAP,16)
	s_waitcnt lgkmcnt(0)
	v_pk_add_f32 v[60:61], v[60:61], v[62:63]
	ds_swizzle_b32 v63, v61 offset:swizzle(SWAP,8)
	ds_swizzle_b32 v62, v60 offset:swizzle(SWAP,8)
	s_waitcnt lgkmcnt(0)
	v_pk_add_f32 v[60:61], v[60:61], v[62:63]
	ds_swizzle_b32 v63, v61 offset:swizzle(SWAP,4)
	ds_swizzle_b32 v62, v60 offset:swizzle(SWAP,4)
	s_waitcnt lgkmcnt(0)
	v_pk_add_f32 v[60:61], v[60:61], v[62:63]
	ds_swizzle_b32 v63, v61 offset:swizzle(SWAP,2)
	ds_swizzle_b32 v62, v60 offset:swizzle(SWAP,2)
	s_waitcnt lgkmcnt(0)
	v_pk_add_f32 v[60:61], v[60:61], v[62:63]
	ds_swizzle_b32 v63, v61 offset:swizzle(SWAP,1)
	ds_swizzle_b32 v62, v60 offset:swizzle(SWAP,1)
	s_waitcnt lgkmcnt(0)
	v_pk_add_f32 v[60:61], v[60:61], v[62:63]
	ds_bpermute_b32 v63, v0, v61
	ds_bpermute_b32 v62, v23, v60
	s_waitcnt lgkmcnt(0)
	v_pk_add_f32 v[60:61], v[60:61], v[62:63]
	s_nop 0
	v_pk_fma_f32 v[60:61], v[60:61], s[58:59], v[154:155] op_sel_hi:[1,0,0]
	s_nop 0
	v_mul_f32_e32 v0, 0x4b800000, v61
	v_cmp_gt_f32_e64 s[2:3], s46, v61
	v_mul_f32_e32 v23, 0x4b800000, v60
	v_cmp_gt_f32_e32 vcc, s46, v60
	v_cndmask_b32_e64 v0, v61, v0, s[2:3]
	v_rsq_f32_e32 v0, v0
	v_cndmask_b32_e32 v23, v60, v23, vcc
	v_rsq_f32_e32 v23, v23
	v_mul_f32_e32 v60, 0x45800000, v0
	v_cndmask_b32_e64 v0, v0, v60, s[2:3]
	v_mul_f32_e32 v61, 0x45800000, v23
	v_cndmask_b32_e32 v60, v23, v61, vcc
	v_pk_mul_f32 v[26:27], v[26:27], v[0:1] op_sel_hi:[1,0]
	v_pk_mul_f32 v[28:29], v[28:29], v[0:1] op_sel_hi:[1,0]
	v_pk_mul_f32 v[30:31], v[30:31], v[0:1] op_sel_hi:[1,0]
	v_pk_mul_f32 v[32:33], v[32:33], v[0:1] op_sel_hi:[1,0]
	v_pk_mul_f32 v[42:43], v[42:43], v[60:61] op_sel_hi:[1,0]
	v_pk_mul_f32 v[44:45], v[44:45], v[60:61] op_sel_hi:[1,0]
	v_pk_mul_f32 v[46:47], v[46:47], v[60:61] op_sel_hi:[1,0]
	v_pk_mul_f32 v[48:49], v[48:49], v[60:61] op_sel_hi:[1,0]
	v_pk_mul_f32 v[34:35], v[34:35], v[0:1] op_sel_hi:[1,0]
	v_pk_mul_f32 v[36:37], v[36:37], v[0:1] op_sel_hi:[1,0]
	v_pk_mul_f32 v[38:39], v[38:39], v[0:1] op_sel_hi:[1,0]
	v_pk_mul_f32 v[40:41], v[40:41], v[0:1] op_sel_hi:[1,0]
	v_pk_mul_f32 v[50:51], v[50:51], v[60:61] op_sel_hi:[1,0]
	v_pk_mul_f32 v[52:53], v[52:53], v[60:61] op_sel_hi:[1,0]
	v_pk_mul_f32 v[54:55], v[54:55], v[60:61] op_sel_hi:[1,0]
	v_pk_mul_f32 v[56:57], v[56:57], v[60:61] op_sel_hi:[1,0]
	v_pk_mul_f32 v[28:29], v[8:9], v[28:29]
	v_pk_mul_f32 v[26:27], v[6:7], v[26:27]
	v_pk_mul_f32 v[32:33], v[4:5], v[32:33]
	v_pk_mul_f32 v[30:31], v[2:3], v[30:31]
	v_pk_mul_f32 v[44:45], v[8:9], v[44:45]
	v_pk_mul_f32 v[42:43], v[6:7], v[42:43]
	v_pk_mul_f32 v[48:49], v[4:5], v[48:49]
	v_pk_mul_f32 v[46:47], v[2:3], v[46:47]
	v_pk_mul_f32 v[36:37], v[16:17], v[36:37]
	v_pk_mul_f32 v[34:35], v[14:15], v[34:35]
	v_pk_mul_f32 v[40:41], v[12:13], v[40:41]
	v_pk_mul_f32 v[38:39], v[10:11], v[38:39]
	v_pk_mul_f32 v[52:53], v[16:17], v[52:53]
	v_pk_mul_f32 v[50:51], v[14:15], v[50:51]
	v_pk_mul_f32 v[56:57], v[12:13], v[56:57]
	v_pk_mul_f32 v[54:55], v[10:11], v[54:55]
	v_cvt_pk_bf16_f32 v26, v26, v27
	v_cvt_pk_bf16_f32 v27, v28, v29
	v_cvt_pk_bf16_f32 v28, v30, v31
	v_cvt_pk_bf16_f32 v29, v32, v33
	v_cvt_pk_bf16_f32 v30, v42, v43
	v_cvt_pk_bf16_f32 v31, v44, v45
	v_cvt_pk_bf16_f32 v32, v46, v47
	v_cvt_pk_bf16_f32 v33, v48, v49
	v_cvt_pk_bf16_f32 v34, v34, v35
	v_cvt_pk_bf16_f32 v35, v36, v37
	v_cvt_pk_bf16_f32 v36, v38, v39
	v_cvt_pk_bf16_f32 v37, v40, v41
	v_cvt_pk_bf16_f32 v38, v50, v51
	v_cvt_pk_bf16_f32 v39, v52, v53
	v_cvt_pk_bf16_f32 v40, v54, v55
	v_cvt_pk_bf16_f32 v41, v56, v57
	global_store_dwordx4 v[24:25], v[26:29], off
	global_store_dwordx4 v[58:59], v[30:33], off
	global_store_dwordx4 v[24:25], v[34:37], off offset:1024
	global_store_dwordx4 v[58:59], v[38:41], off offset:1024
.Ln1_done:
.LBB0_225:
	s_or_b64 exec, exec, s[4:5]
	s_barrier
	s_mov_b64 s[2:3], exec
	v_readlane_b32 s0, v253, 57
	v_readlane_b32 s1, v253, 58
	s_and_b64 s[0:1], s[2:3], s[0:1]
	s_mov_b64 exec, s[0:1]
	s_cbranch_execz .LBB0_235
	buffer_wbl2 sc1
	s_load_dwordx2 s[4:5], s[56:57], -0x8
	s_load_dword s0, s[56:57], 0x0
	v_readlane_b32 s1, v253, 55
	s_waitcnt lgkmcnt(0)
	s_and_b32 s1, s1, 7
	s_add_i32 s6, s0, 7
	s_sub_i32 s6, s6, s1
	s_lshr_b32 s6, s6, 3
	s_min_u32 s7, s0, 8
	s_lshl_b32 s1, s1, 2
	s_addk_i32 s1, 0x88
	v_mov_b32_e32 v2, s1
	global_load_dword v0, v1, s[4:5] sc1
	v_mov_b32_e32 v3, 1
	s_waitcnt vmcnt(0)
	v_and_b32_e32 v0, 0xffff0000, v0
	global_atomic_add v3, v2, v3, s[4:5] sc0
	s_waitcnt vmcnt(0)
	v_and_b32_e32 v3, 0xffff, v3
	s_nop 0
	v_readfirstlane_b32 s1, v3
	s_nop 3
	s_add_i32 s0, s6, -1
	s_cmp_lg_u32 s1, s0
	s_cbranch_scc1 .Lgb_poll_0
	s_sub_i32 s1, 0x10000, s6
	v_mov_b32_e32 v3, s1
	global_atomic_add v3, v2, v3, s[4:5] sc0
	s_waitcnt vmcnt(0)
	v_mov_b32_e32 v3, 1
	global_atomic_add v3, v1, v3, s[4:5] sc0
	s_waitcnt vmcnt(0)
	v_and_b32_e32 v3, 0xffff, v3
	s_nop 0
	v_readfirstlane_b32 s1, v3
	s_nop 3
	s_add_i32 s0, s7, -1
	s_cmp_lg_u32 s1, s0
	s_cbranch_scc1 .Lgb_poll_0
	s_sub_i32 s1, 0x10000, s7
	v_mov_b32_e32 v3, s1
	global_atomic_add v1, v3, s[4:5]

; __device__ __forceinline__ int ltid() { return launder((int)threadIdx.x); }
; #define G_STAGE(P, BASE, LD, br, kt) do { const char* _gp = (const char*)((BASE) + (size_t)(br) * (LD) + (size_t)(kt) * BK); \
;     _Pragma("unroll") for (int _i = 0; _i < 2; ++_i)   \
;       __builtin_amdgcn_global_load_lds((const unsigned*)(_gp + (size_t)_i * 128 * (LD) + off_##BASE), (unsigned*)((P) + tid * 16 + _i * 8192), 16, 0, 0); } while (0)
; #define WAIT_V(n) asm volatile("s_waitcnt vmcnt(" #n ")" ::: "memory")
; #define BAR __builtin_amdgcn_s_barrier()
;   const int tid = ltid(), wid = tid >> 6, lane = tid & 63, wr = wid >> 2, wc = wid & 3, fr = lane & 15, fq = lane >> 4;
;   f32x4 acc[2][2][4][2];
; #pragma unroll
;   for (int a = 0; a < 2; ++a)
; #pragma unroll
;     for (int b = 0; b < 2; ++b)
; #pragma unroll
;       for (int m = 0; m < 4; ++m)
; #pragma unroll
;         for (int n = 0; n < 2; ++n) acc[a][b][m][n] = (f32x4){0.f, 0.f, 0.f, 0.f};
;   bf16x8 At[4][2], B0[2][2], B1[2][2];
;   const int nt = K / BK;
;   unsigned off_A, off_Bt;
;   { int r_, c_; stage_rc(tid * 16, r_, c_); off_A = (unsigned)(r_ * lda + c_) * 2u; off_Bt = (unsigned)(r_ * ldb + c_) * 2u; }
;   if (!prestaged) {
;     G_STAGE(G_SB(0, 0), Bt, ldb, bcol, 0); G_STAGE(G_SA(0, 0), A, lda, brow, 0);
;     G_STAGE(G_SB(0, 1), Bt, ldb, bcol + HALF, 0); G_STAGE(G_SA(0, 1), A, lda, brow + HALF, 0);
;   }
;   if (wr == 1) BAR;
;   WAIT_V(4); BAR;
;   G_STAGE(G_SB(1, 0), Bt, ldb, bcol, 1); G_STAGE(G_SA(1, 0), A, lda, brow, 1); G_STAGE(G_SB(1, 1), Bt, ldb, bcol + HALF, 1);
;   WAIT_V(6); BAR;
.LBB0_1457:
	s_or_b64 exec, exec, s[12:13]
	s_lshl_b64 s[12:13], s[90:91], 11
	s_add_u32 s14, s8, s12
	v_readlane_b32 s22, v254, 47
	s_addc_u32 s15, s9, s13
	v_lshl_add_u64 v[6:7], s[14:15], 0, v[0:1]
	v_add_u32_e32 v149, s22, v142
	s_mov_b64 s[24:25], 0x80
	v_readfirstlane_b32 s11, v149
	v_add_u32_e32 v150, 0x2000, v149
	v_lshl_add_u64 v[8:9], v[6:7], 0, s[24:25]
	s_mov_b32 m0, s11
	v_readfirstlane_b32 s11, v150
	s_waitcnt vmcnt(4)
	s_barrier
	global_load_lds_dwordx4 v[8:9], off
	s_mov_b32 m0, s11
	s_mov_b32 s11, s91
	s_lshl_b64 s[14:15], s[10:11], 11
	v_readlane_b32 s20, v253, 62
	s_mov_b64 s[26:27], 0x20080
	v_readlane_b32 s21, v253, 63
	s_add_u32 s20, s20, s14
	v_lshl_add_u64 v[6:7], v[6:7], 0, s[26:27]
	s_addc_u32 s21, s21, s15
	global_load_lds_dwordx4 v[6:7], off
	v_lshl_add_u64 v[6:7], s[20:21], 0, v[0:1]
	v_add_u32_e32 v151, 0x8000, v137
	s_or_b32 s20, s90, 0x80
	s_mov_b32 s21, s91
	v_readfirstlane_b32 s11, v151
	v_add_u32_e32 v152, 0xa000, v137
	s_lshl_b64 s[20:21], s[20:21], 11
	v_lshl_add_u64 v[8:9], v[6:7], 0, s[24:25]
	s_mov_b32 m0, s11
	v_readfirstlane_b32 s11, v152
	s_add_u32 s20, s8, s20
	global_load_lds_dwordx4 v[8:9], off
	v_lshl_add_u64 v[6:7], v[6:7], 0, s[26:27]
	s_mov_b32 m0, s11
	s_addc_u32 s21, s9, s21
	global_load_lds_dwordx4 v[6:7], off
	v_lshl_add_u64 v[6:7], s[20:21], 0, v[0:1]
	v_readlane_b32 s20, v254, 48
	v_lshl_add_u64 v[8:9], v[6:7], 0, s[24:25]
	v_lshl_add_u64 v[6:7], v[6:7], 0, s[26:27]
	v_add_u32_e32 v156, s20, v142
	v_add_u32_e32 v166, 0x2000, v156
	v_readfirstlane_b32 s11, v156
	s_mov_b32 m0, s11
	v_readfirstlane_b32 s11, v166
	global_load_lds_dwordx4 v[8:9], off
	s_mov_b32 m0, s11
	v_and_b32_e32 v218, 15, v138
	global_load_lds_dwordx4 v[6:7], off
	v_bfe_u32 v10, v138, 4, 2
	v_lshlrev_b32_e32 v8, 2, v138
	v_lshlrev_b32_e32 v130, 4, v10
	v_lshlrev_b32_e32 v7, 6, v218
	v_and_b32_e32 v8, 32, v8
	v_lshlrev_b32_e32 v16, 14, v2
	v_bitop3_b32 v7, v130, v8, v7 bitop3:0x36
	s_add_i32 s11, 0, 0x10000
	v_readlane_b32 s19, v254, 46
	v_and_b32_e32 v16, 0xffff8000, v16
	v_add_u32_e32 v11, s22, v7
	v_add_u32_e32 v10, s19, v7
	v_add_u32_e32 v12, s20, v7
	v_lshlrev_b32_e32 v13, 6, v138
	s_movk_i32 s19, 0x3c0
	v_lshl_add_u32 v3, v3, 11, v16
	v_and_b32_e32 v2, 1, v2
	s_add_u32 s12, s0, s12
	v_readlane_b32 s20, v253, 16
	v_bfe_u32 v139, v138, 6, 2
	s_waitcnt vmcnt(6)
	v_lshlrev_b32_e32 v215, 6, v5
	v_lshlrev_b32_e32 v5, 13, v5
	v_and_or_b32 v13, v13, s19, v130
	v_lshl_or_b32 v2, v2, 6, v3
	s_addc_u32 s13, s1, s13
	v_readlane_b32 s26, v253, 22
	v_lshlrev_b32_e32 v6, 12, v139
	v_add_u32_e32 v9, s11, v7
	v_add_u32_e32 v7, 0, v7
	v_xad_u32 v8, v13, v8, 0
	v_or_b32_e32 v13, 0x800, v5
	v_or_b32_e32 v14, 0x1000, v5
	v_or_b32_e32 v15, 0x1800, v5
	v_lshl_add_u32 v132, v4, 1, v2
	v_readlane_b32 s22, v253, 18
	v_readlane_b32 s23, v253, 19
	v_readlane_b32 s24, v253, 20
	v_readlane_b32 s25, v253, 21
	v_readlane_b32 s27, v253, 23
	s_add_u32 s14, s26, s14
	v_mov_b32_e32 v2, 0
	v_mov_b32_e32 v133, v1
	s_addc_u32 s15, s27, s15
	s_mov_b32 s19, -2
	v_add_u32_e32 v167, v9, v6
	v_add_u32_e32 v146, v7, v5
	v_add_u32_e32 v145, v8, v13
	v_add_u32_e32 v144, v8, v14
	v_add_u32_e32 v143, v8, v15
	v_add_u32_e32 v153, v10, v6
	v_add_u32_e32 v148, v11, v6
	v_add_u32_e32 v147, v12, v6
	v_mov_b32_e32 v3, v2
	v_mov_b32_e32 v4, v2
	v_mov_b32_e32 v5, v2
	v_mov_b32_e32 v6, v2
	v_mov_b32_e32 v7, v2
	v_mov_b32_e32 v8, v2
	v_mov_b32_e32 v9, v2
	v_mov_b32_e32 v10, v2
	v_mov_b32_e32 v11, v2
	v_mov_b32_e32 v12, v2
	v_mov_b32_e32 v13, v2
	v_mov_b32_e32 v14, v2
	v_mov_b32_e32 v15, v2
	v_mov_b32_e32 v16, v2
	v_mov_b32_e32 v17, v2
	v_mov_b32_e32 v18, v2
	v_mov_b32_e32 v19, v2
	v_mov_b32_e32 v20, v2
	v_mov_b32_e32 v21, v2
	v_mov_b32_e32 v22, v2
	v_mov_b32_e32 v23, v2
	v_mov_b32_e32 v24, v2
	v_mov_b32_e32 v25, v2
	v_mov_b32_e32 v26, v2
	v_mov_b32_e32 v27, v2
	v_mov_b32_e32 v28, v2
	v_mov_b32_e32 v29, v2
	v_mov_b32_e32 v30, v2
	v_mov_b32_e32 v31, v2
	v_mov_b32_e32 v32, v2
	v_mov_b32_e32 v33, v2
	v_mov_b32_e32 v34, v2
	v_mov_b32_e32 v35, v2
	v_mov_b32_e32 v36, v2
	v_mov_b32_e32 v37, v2
	v_mov_b32_e32 v38, v2
	v_mov_b32_e32 v39, v2
	v_mov_b32_e32 v40, v2
	v_mov_b32_e32 v41, v2
	v_mov_b32_e32 v42, v2
	v_mov_b32_e32 v43, v2
	v_mov_b32_e32 v44, v2
	v_mov_b32_e32 v45, v2
	v_mov_b32_e32 v46, v2
	v_mov_b32_e32 v47, v2
	v_mov_b32_e32 v48, v2
	v_mov_b32_e32 v49, v2
	v_mov_b32_e32 v50, v2
	v_mov_b32_e32 v51, v2
	v_mov_b32_e32 v52, v2
	v_mov_b32_e32 v53, v2
	v_mov_b32_e32 v54, v2
	v_mov_b32_e32 v55, v2
	v_mov_b32_e32 v56, v2
	v_mov_b32_e32 v57, v2
	v_mov_b32_e32 v58, v2
	v_mov_b32_e32 v59, v2
	v_mov_b32_e32 v60, v2
	v_mov_b32_e32 v61, v2
	v_mov_b32_e32 v62, v2
	v_mov_b32_e32 v63, v2
	v_mov_b32_e32 v64, v2
	v_mov_b32_e32 v65, v2
	v_mov_b32_e32 v66, v2
	v_mov_b32_e32 v67, v2
	v_mov_b32_e32 v68, v2
	v_mov_b32_e32 v69, v2
	v_mov_b32_e32 v70, v2
	v_mov_b32_e32 v71, v2
	v_mov_b32_e32 v72, v2
	v_mov_b32_e32 v73, v2
	v_mov_b32_e32 v74, v2
	v_mov_b32_e32 v75, v2
	v_mov_b32_e32 v76, v2
	v_mov_b32_e32 v77, v2
	v_mov_b32_e32 v78, v2
	v_mov_b32_e32 v79, v2
	v_mov_b32_e32 v80, v2
	v_mov_b32_e32 v81, v2
	s_waitcnt vmcnt(6)
	v_mov_b32_e32 v82, v2
	v_mov_b32_e32 v83, v2
	v_mov_b32_e32 v84, v2
	v_mov_b32_e32 v85, v2
	v_mov_b32_e32 v86, v2
	v_mov_b32_e32 v87, v2
	v_mov_b32_e32 v88, v2
	v_mov_b32_e32 v89, v2
	v_mov_b32_e32 v90, v2
	v_mov_b32_e32 v91, v2
	v_mov_b32_e32 v92, v2
	v_mov_b32_e32 v93, v2
	v_mov_b32_e32 v94, v2
	v_mov_b32_e32 v95, v2
	v_mov_b32_e32 v96, v2
	v_mov_b32_e32 v97, v2
	v_mov_b32_e32 v98, v2
	v_mov_b32_e32 v99, v2
	v_mov_b32_e32 v100, v2
	v_mov_b32_e32 v101, v2
	v_mov_b32_e32 v102, v2
	v_mov_b32_e32 v103, v2
	v_mov_b32_e32 v104, v2
	v_mov_b32_e32 v105, v2
	v_mov_b32_e32 v106, v2
	v_mov_b32_e32 v107, v2
	v_mov_b32_e32 v108, v2
	v_mov_b32_e32 v109, v2
	v_mov_b32_e32 v110, v2
	v_mov_b32_e32 v111, v2
	v_mov_b32_e32 v112, v2
	v_mov_b32_e32 v113, v2
	v_mov_b32_e32 v114, v2
	v_mov_b32_e32 v115, v2
	v_mov_b32_e32 v116, v2
	v_mov_b32_e32 v117, v2
	v_mov_b32_e32 v118, v2
	v_mov_b32_e32 v119, v2
	v_mov_b32_e32 v120, v2
	v_mov_b32_e32 v121, v2
	v_mov_b32_e32 v122, v2
	v_mov_b32_e32 v123, v2
	v_mov_b32_e32 v124, v2
	v_mov_b32_e32 v125, v2
	v_mov_b32_e32 v126, v2
	v_mov_b32_e32 v127, v2
	v_mov_b32_e32 v128, v2
	v_mov_b32_e32 v129, v2
	s_mov_b64 s[22:23], 0xb0c2080
	s_mov_b64 s[24:25], 0xb0e2080
	s_mov_b64 s[26:27], 0xb082100
	s_mov_b64 s[28:29], 0xb0a2100
	s_mov_b64 s[30:31], 0xb0c2100
	s_mov_b64 s[34:35], 0xb0e2100
	s_mov_b64 s[36:37], 0xb082180
	s_mov_b64 s[38:39], 0xb0a2180
	s_mov_b64 s[40:41], 0xa82100
	s_mov_b64 s[42:43], 0xaa2100
	s_mov_b64 s[44:45], 0xac2100
	s_mov_b64 s[60:61], 0xae2100
	s_mov_b64 s[62:63], 0xa82180
	s_mov_b64 s[64:65], 0xaa2180
	s_mov_b64 s[66:67], 0xac2180
	s_mov_b64 s[68:69], 0xae2180
	s_barrier
	v_readlane_b32 s21, v253, 17

; __device__ __forceinline__ int ltid() { return launder((int)threadIdx.x); }
; #define G_STAGE(P, BASE, LD, br, kt) do { const char* _gp = (const char*)((BASE) + (size_t)(br) * (LD) + (size_t)(kt) * BK); \
;     _Pragma("unroll") for (int _i = 0; _i < 2; ++_i)   \
;       __builtin_amdgcn_global_load_lds((const unsigned*)(_gp + (size_t)_i * 128 * (LD) + off_##BASE), (unsigned*)((P) + tid * 16 + _i * 8192), 16, 0, 0); } while (0)
; #define WAIT_V(n) asm volatile("s_waitcnt vmcnt(" #n ")" ::: "memory")
; #define BAR __builtin_amdgcn_s_barrier()
;   const int tid = ltid(), wid = tid >> 6, lane = tid & 63, wr = wid >> 2, wc = wid & 3, fr = lane & 15, fq = lane >> 4;
;   f32x4 acc[2][2][4][2];
; #pragma unroll
;   for (int a = 0; a < 2; ++a)
; #pragma unroll
;     for (int b = 0; b < 2; ++b)
; #pragma unroll
;       for (int m = 0; m < 4; ++m)
; #pragma unroll
;         for (int n = 0; n < 2; ++n) acc[a][b][m][n] = (f32x4){0.f, 0.f, 0.f, 0.f};
;   bf16x8 At[4][2], B0[2][2], B1[2][2];
;   const int nt = K / BK;
;   unsigned off_A, off_Bt;
;   { int r_, c_; stage_rc(tid * 16, r_, c_); off_A = (unsigned)(r_ * lda + c_) * 2u; off_Bt = (unsigned)(r_ * ldb + c_) * 2u; }
;   if (!prestaged) {
;     G_STAGE(G_SB(0, 0), Bt, ldb, bcol, 0); G_STAGE(G_SA(0, 0), A, lda, brow, 0);
;     G_STAGE(G_SB(0, 1), Bt, ldb, bcol + HALF, 0); G_STAGE(G_SA(0, 1), A, lda, brow + HALF, 0);
;   }
;   if (wr == 1) BAR;
;   WAIT_V(4); BAR;
;   G_STAGE(G_SB(1, 0), Bt, ldb, bcol, 1); G_STAGE(G_SA(1, 0), A, lda, brow, 1); G_STAGE(G_SB(1, 1), Bt, ldb, bcol + HALF, 1);
;   WAIT_V(6); BAR;
.LBB0_1481:
	s_or_b64 exec, exec, s[10:11]
	s_lshl_b64 s[10:11], s[90:91], 11
	v_readlane_b32 s18, v253, 51
	v_readlane_b32 s19, v253, 52
	s_add_u32 s12, s18, s10
	v_readlane_b32 s20, v254, 47
	s_addc_u32 s13, s19, s11
	v_lshl_add_u64 v[6:7], s[12:13], 0, v[0:1]
	v_add_u32_e32 v149, s20, v142
	s_mov_b64 s[22:23], 0x80
	v_readfirstlane_b32 s9, v149
	v_add_u32_e32 v150, 0x2000, v149
	v_lshl_add_u64 v[8:9], v[6:7], 0, s[22:23]
	s_mov_b32 m0, s9
	v_readfirstlane_b32 s9, v150
	s_waitcnt vmcnt(4)
	s_barrier
	global_load_lds_dwordx4 v[8:9], off
	s_mov_b32 m0, s9
	s_mov_b32 s9, s91
	s_lshl_b64 s[12:13], s[8:9], 11
	v_readlane_b32 s16, v253, 62
	s_mov_b64 s[24:25], 0x20080
	v_readlane_b32 s17, v253, 63
	s_add_u32 s16, s16, s12
	v_lshl_add_u64 v[6:7], v[6:7], 0, s[24:25]
	s_addc_u32 s17, s17, s13
	global_load_lds_dwordx4 v[6:7], off
	v_lshl_add_u64 v[6:7], s[16:17], 0, v[0:1]
	v_add_u32_e32 v151, 0x8000, v137
	s_or_b32 s16, s90, 0x80
	s_mov_b32 s17, s91
	v_readfirstlane_b32 s9, v151
	v_add_u32_e32 v152, 0xa000, v137
	s_lshl_b64 s[16:17], s[16:17], 11
	v_lshl_add_u64 v[8:9], v[6:7], 0, s[22:23]
	s_mov_b32 m0, s9
	v_readfirstlane_b32 s9, v152
	s_add_u32 s16, s18, s16
	global_load_lds_dwordx4 v[8:9], off
	v_lshl_add_u64 v[6:7], v[6:7], 0, s[24:25]
	s_mov_b32 m0, s9
	s_addc_u32 s17, s19, s17
	global_load_lds_dwordx4 v[6:7], off
	v_lshl_add_u64 v[6:7], s[16:17], 0, v[0:1]
	v_readlane_b32 s16, v254, 48
	v_lshl_add_u64 v[8:9], v[6:7], 0, s[22:23]
	v_lshl_add_u64 v[6:7], v[6:7], 0, s[24:25]
	v_add_u32_e32 v156, s16, v142
	v_add_u32_e32 v166, 0x2000, v156
	v_readfirstlane_b32 s9, v156
	s_mov_b32 m0, s9
	v_readfirstlane_b32 s9, v166
	global_load_lds_dwordx4 v[8:9], off
	s_mov_b32 m0, s9
	v_and_b32_e32 v140, 15, v138
	global_load_lds_dwordx4 v[6:7], off
	v_bfe_u32 v10, v138, 4, 2
	v_lshlrev_b32_e32 v8, 2, v138
	v_lshlrev_b32_e32 v130, 4, v10
	v_lshlrev_b32_e32 v7, 6, v140
	v_and_b32_e32 v8, 32, v8
	v_bitop3_b32 v7, v130, v8, v7 bitop3:0x36
	v_add_u32_e32 v11, s20, v7
	v_add_u32_e32 v12, s16, v7
	v_lshlrev_b32_e32 v16, 14, v2
	v_readlane_b32 s16, v253, 16
	s_add_i32 s9, 0, 0x10000
	v_readlane_b32 s15, v254, 46
	v_and_b32_e32 v16, 0xffff8000, v16
	v_readlane_b32 s22, v253, 22
	v_add_u32_e32 v10, s15, v7
	v_lshlrev_b32_e32 v13, 6, v138
	s_movk_i32 s15, 0x3c0
	v_lshl_add_u32 v3, v3, 11, v16
	v_and_b32_e32 v2, 1, v2
	v_readlane_b32 s23, v253, 23
	s_add_u32 s10, s22, s10
	v_bfe_u32 v139, v138, 6, 2
	s_waitcnt vmcnt(6)
	v_lshlrev_b32_e32 v141, 6, v5
	v_lshlrev_b32_e32 v5, 13, v5
	v_and_or_b32 v13, v13, s15, v130
	v_lshl_or_b32 v2, v2, 6, v3
	s_addc_u32 s11, s23, s11
	v_lshlrev_b32_e32 v6, 12, v139
	v_add_u32_e32 v9, s9, v7
	v_add_u32_e32 v7, 0, v7
	v_xad_u32 v8, v13, v8, 0
	v_or_b32_e32 v13, 0x800, v5
	v_or_b32_e32 v14, 0x1000, v5
	v_or_b32_e32 v15, 0x1800, v5
	v_lshl_add_u32 v132, v4, 1, v2
	v_readlane_b32 s18, v253, 18
	v_readlane_b32 s19, v253, 19
	v_readlane_b32 s20, v253, 20
	v_readlane_b32 s21, v253, 21
	s_add_u32 s12, s22, s12
	v_mov_b32_e32 v2, 0
	v_mov_b32_e32 v133, v1
	s_addc_u32 s13, s23, s13
	s_mov_b32 s15, -2
	v_add_u32_e32 v167, v9, v6
	v_add_u32_e32 v146, v7, v5
	v_add_u32_e32 v145, v8, v13
	v_add_u32_e32 v144, v8, v14
	v_add_u32_e32 v143, v8, v15
	v_add_u32_e32 v153, v10, v6
	v_add_u32_e32 v148, v11, v6
	v_add_u32_e32 v147, v12, v6
	v_mov_b32_e32 v3, v2
	v_mov_b32_e32 v4, v2
	v_mov_b32_e32 v5, v2
	v_mov_b32_e32 v6, v2
	v_mov_b32_e32 v7, v2
	v_mov_b32_e32 v8, v2
	v_mov_b32_e32 v9, v2
	v_mov_b32_e32 v10, v2
	v_mov_b32_e32 v11, v2
	v_mov_b32_e32 v12, v2
	v_mov_b32_e32 v13, v2
	v_mov_b32_e32 v14, v2
	v_mov_b32_e32 v15, v2
	v_mov_b32_e32 v16, v2
	v_mov_b32_e32 v17, v2
	v_mov_b32_e32 v18, v2
	v_mov_b32_e32 v19, v2
	v_mov_b32_e32 v20, v2
	v_mov_b32_e32 v21, v2
	v_mov_b32_e32 v22, v2
	v_mov_b32_e32 v23, v2
	v_mov_b32_e32 v24, v2
	v_mov_b32_e32 v25, v2
	v_mov_b32_e32 v26, v2
	v_mov_b32_e32 v27, v2
	v_mov_b32_e32 v28, v2
	v_mov_b32_e32 v29, v2
	v_mov_b32_e32 v30, v2
	v_mov_b32_e32 v31, v2
	v_mov_b32_e32 v32, v2
	v_mov_b32_e32 v33, v2
	v_mov_b32_e32 v34, v2
	v_mov_b32_e32 v35, v2
	v_mov_b32_e32 v36, v2
	v_mov_b32_e32 v37, v2
	v_mov_b32_e32 v38, v2
	v_mov_b32_e32 v39, v2
	v_mov_b32_e32 v40, v2
	v_mov_b32_e32 v41, v2
	v_mov_b32_e32 v42, v2
	v_mov_b32_e32 v43, v2
	v_mov_b32_e32 v44, v2
	v_mov_b32_e32 v45, v2
	v_mov_b32_e32 v46, v2
	v_mov_b32_e32 v47, v2
	v_mov_b32_e32 v48, v2
	v_mov_b32_e32 v49, v2
	v_mov_b32_e32 v50, v2
	v_mov_b32_e32 v51, v2
	v_mov_b32_e32 v52, v2
	v_mov_b32_e32 v53, v2
	v_mov_b32_e32 v54, v2
	v_mov_b32_e32 v55, v2
	v_mov_b32_e32 v56, v2
	v_mov_b32_e32 v57, v2
	v_mov_b32_e32 v58, v2
	v_mov_b32_e32 v59, v2
	v_mov_b32_e32 v60, v2
	v_mov_b32_e32 v61, v2
	v_mov_b32_e32 v62, v2
	v_mov_b32_e32 v63, v2
	v_mov_b32_e32 v64, v2
	v_mov_b32_e32 v65, v2
	v_mov_b32_e32 v66, v2
	v_mov_b32_e32 v67, v2
	v_mov_b32_e32 v68, v2
	v_mov_b32_e32 v69, v2
	v_mov_b32_e32 v70, v2
	v_mov_b32_e32 v71, v2
	v_mov_b32_e32 v72, v2
	v_mov_b32_e32 v73, v2
	v_mov_b32_e32 v74, v2
	v_mov_b32_e32 v75, v2
	v_mov_b32_e32 v76, v2
	v_mov_b32_e32 v77, v2
	v_mov_b32_e32 v78, v2
	v_mov_b32_e32 v79, v2
	v_mov_b32_e32 v80, v2
	v_mov_b32_e32 v81, v2
	s_waitcnt vmcnt(6)
	v_mov_b32_e32 v82, v2
	v_mov_b32_e32 v83, v2
	v_mov_b32_e32 v84, v2
	v_mov_b32_e32 v85, v2
	v_mov_b32_e32 v86, v2
	v_mov_b32_e32 v87, v2
	v_mov_b32_e32 v88, v2
	v_mov_b32_e32 v89, v2
	v_mov_b32_e32 v90, v2
	v_mov_b32_e32 v91, v2
	v_mov_b32_e32 v92, v2
	v_mov_b32_e32 v93, v2
	v_mov_b32_e32 v94, v2
	v_mov_b32_e32 v95, v2
	v_mov_b32_e32 v96, v2
	v_mov_b32_e32 v97, v2
	v_mov_b32_e32 v98, v2
	v_mov_b32_e32 v99, v2
	v_mov_b32_e32 v100, v2
	v_mov_b32_e32 v101, v2
	v_mov_b32_e32 v102, v2
	v_mov_b32_e32 v103, v2
	v_mov_b32_e32 v104, v2
	v_mov_b32_e32 v105, v2
	v_mov_b32_e32 v106, v2
	v_mov_b32_e32 v107, v2
	v_mov_b32_e32 v108, v2
	v_mov_b32_e32 v109, v2
	v_mov_b32_e32 v110, v2
	v_mov_b32_e32 v111, v2
	v_mov_b32_e32 v112, v2
	v_mov_b32_e32 v113, v2
	v_mov_b32_e32 v114, v2
	v_mov_b32_e32 v115, v2
	v_mov_b32_e32 v116, v2
	v_mov_b32_e32 v117, v2
	v_mov_b32_e32 v118, v2
	v_mov_b32_e32 v119, v2
	v_mov_b32_e32 v120, v2
	v_mov_b32_e32 v121, v2
	v_mov_b32_e32 v122, v2
	v_mov_b32_e32 v123, v2
	v_mov_b32_e32 v124, v2
	v_mov_b32_e32 v125, v2
	v_mov_b32_e32 v126, v2
	v_mov_b32_e32 v127, v2
	v_mov_b32_e32 v128, v2
	v_mov_b32_e32 v129, v2
	s_mov_b64 s[18:19], 0xb0c2080
	s_mov_b64 s[20:21], 0xb0e2080
	s_mov_b64 s[22:23], 0xb082100
	s_mov_b64 s[24:25], 0xb0a2100
	s_mov_b64 s[26:27], 0xb0c2100
	s_mov_b64 s[28:29], 0xb0e2100
	s_mov_b64 s[30:31], 0xb082180
	s_mov_b64 s[34:35], 0xb0a2180
	s_mov_b64 s[36:37], 0xa82100
	s_mov_b64 s[38:39], 0xaa2100
	s_mov_b64 s[40:41], 0xac2100
	s_mov_b64 s[42:43], 0xae2100
	s_mov_b64 s[44:45], 0xa82180
	s_mov_b64 s[60:61], 0xaa2180
	s_mov_b64 s[62:63], 0xac2180
	s_mov_b64 s[64:65], 0xae2180
	s_barrier
	v_readlane_b32 s17, v253, 17
